# RWKV scan consumer waves at raised priority over the producer waves sharing their SIMDs
# baseline (speedup 1.0000x reference)
.LBB0_1746:
	s_and_b64 vcc, exec, s[6:7]
	s_cbranch_vccz .LBB0_1797
	v_readlane_b32 s4, v254, 37
	v_readlane_b32 s7, v254, 40
	s_cmp_lt_u32 s7, 2
	v_readlane_b32 s5, v254, 38
	v_readlane_b32 s6, v254, 39
	s_cbranch_scc0 .LBB0_1797
	s_ashr_i32 s18, s28, 5
	s_movk_i32 s0, 0x100
	s_waitcnt vmcnt(0)
	v_and_b32_e32 v4, 63, v34
	v_lshrrev_b32_e32 v23, 6, v34
	s_and_b32 s27, s28, 1
	s_bfe_u32 s26, s28, 0x40001
	s_ashr_i32 s19, s18, 31
	v_cmp_gt_u32_e32 vcc, s0, v34
	s_and_saveexec_b64 s[0:1], vcc
	s_xor_b64 s[20:21], exec, s[0:1]
	s_cbranch_execz .LBB0_1752
	v_lshrrev_b32_e32 v1, 4, v4
	v_lshlrev_b32_e32 v1, 1, v1
	v_lshl_or_b32 v1, v23, 3, v1
	v_and_b32_e32 v2, 3, v4
	v_bfe_u32 v3, v4, 3, 1
	v_lshl_or_b32 v2, v3, 2, v2
	v_bfe_u32 v3, v4, 2, 1
	v_and_b32_e32 v10, 15, v4
	s_waitcnt lgkmcnt(0)
	s_barrier
	v_add_u32_e32 v3, v1, v3
	v_lshlrev_b32_e32 v3, 2, v3
	v_lshlrev_b32_e32 v12, 7, v2
	s_add_i32 s0, 0, 0x18000
	v_lshlrev_b32_e32 v10, 4, v10
	v_cmp_eq_u32_e32 vcc, 7, v2
	v_add3_u32 v11, s0, v12, v3
	v_cmp_eq_u32_e64 s[0:1], 0, v2
	v_cmp_eq_u32_e64 s[6:7], 1, v2
	v_cmp_eq_u32_e64 s[8:9], 2, v2
	v_cmp_eq_u32_e64 s[10:11], 3, v2
	v_cmp_eq_u32_e64 s[12:13], 4, v2
	v_cmp_eq_u32_e64 s[14:15], 5, v2
	v_cmp_eq_u32_e64 s[16:17], 6, v2
	v_mov_b32_e32 v2, 0
	s_lshl_b32 s5, s27, 7
	s_mov_b32 s22, 0
	v_mov_b32_e32 v3, v2
	v_mov_b32_e32 v4, v2
	v_mov_b32_e32 v5, v2
	v_mov_b32_e32 v6, v2
	v_mov_b32_e32 v7, v2
	v_mov_b32_e32 v8, v2
	v_mov_b32_e32 v9, v2
	s_setprio 3
.LBB0_1750:
	s_and_b32 s23, s22, 1
	s_mul_i32 s2, s23, 0xc000
	s_add_i32 s2, s2, 0
	v_add_u32_e32 v20, s2, v10
	s_add_i32 s2, s2, s5
	v_lshl_add_u32 v21, v1, 2, s2
	ds_read_b128 v[36:39], v20 offset:0
	ds_read_b128 v[40:43], v20 offset:8192
	ds_read_b64 v[56:57], v21 offset:40960
	ds_read_b128 v[48:51], v20 offset:24576
	ds_read_b128 v[44:47], v20 offset:16384
	ds_read_b128 v[52:55], v20 offset:32768
	s_waitcnt lgkmcnt(0)
	v_pk_mul_f32 v[22:23], v[2:3], v[36:37] op_sel:[0,0] op_sel_hi:[1,0]
	ds_read_b128 v[60:63], v20 offset:256
	v_pk_fma_f32 v[22:23], v[4:5], v[36:37], v[22:23] op_sel:[0,1,0] op_sel_hi:[1,1,1]
	ds_read_b128 v[64:67], v20 offset:8448
	v_pk_fma_f32 v[22:23], v[6:7], v[38:39], v[22:23] op_sel:[0,0,0] op_sel_hi:[1,0,1]
	ds_read_b64 v[80:81], v21 offset:41216
	v_pk_fma_f32 v[22:23], v[8:9], v[38:39], v[22:23] op_sel:[0,1,0] op_sel_hi:[1,1,1]
	ds_read_b128 v[72:75], v20 offset:24832
	ds_read_b128 v[68:71], v20 offset:16640
	ds_read_b128 v[76:79], v20 offset:33024
	v_add_f32_dpp v22, v22, v22 quad_perm:[1,0,3,2] row_mask:0xf bank_mask:0xf
	v_add_f32_dpp v23, v23, v23 quad_perm:[1,0,3,2] row_mask:0xf bank_mask:0xf
	v_pk_mul_f32 v[84:85], v[2:3], v[40:41] op_sel:[0,0] op_sel_hi:[1,0]
	v_pk_mul_f32 v[86:87], v[4:5], v[40:41] op_sel:[0,1] op_sel_hi:[1,1]
	v_add_f32_dpp v22, v22, v22 quad_perm:[2,3,0,1] row_mask:0xf bank_mask:0xf
	v_add_f32_dpp v23, v23, v23 quad_perm:[2,3,0,1] row_mask:0xf bank_mask:0xf
	v_pk_mul_f32 v[88:89], v[6:7], v[42:43] op_sel:[0,0] op_sel_hi:[1,0]
	v_pk_mul_f32 v[90:91], v[8:9], v[42:43] op_sel:[0,1] op_sel_hi:[1,1]
	v_add_f32_dpp v22, v22, v22 row_half_mirror row_mask:0xf bank_mask:0xf
	v_add_f32_dpp v23, v23, v23 row_half_mirror row_mask:0xf bank_mask:0xf
	v_pk_fma_f32 v[84:85], v[48:49], v[56:57], v[84:85] op_sel:[0,0,0] op_sel_hi:[0,1,1]
	v_pk_fma_f32 v[86:87], v[48:49], v[56:57], v[86:87] op_sel:[1,0,0] op_sel_hi:[1,1,1]
	v_add_f32_dpp v22, v22, v22 row_mirror row_mask:0xf bank_mask:0xf
	v_add_f32_dpp v23, v23, v23 row_mirror row_mask:0xf bank_mask:0xf
	v_pk_fma_f32 v[88:89], v[50:51], v[56:57], v[88:89] op_sel:[0,0,0] op_sel_hi:[0,1,1]
	v_pk_fma_f32 v[90:91], v[50:51], v[56:57], v[90:91] op_sel:[1,0,0] op_sel_hi:[1,1,1]
	v_pk_fma_f32 v[2:3], v[44:45], v[22:23], v[84:85] op_sel:[0,0,0] op_sel_hi:[0,1,1] neg_lo:[1,0,0] neg_hi:[1,0,0]
	v_pk_fma_f32 v[4:5], v[44:45], v[22:23], v[86:87] op_sel:[1,0,0] op_sel_hi:[1,1,1] neg_lo:[1,0,0] neg_hi:[1,0,0]
	v_pk_fma_f32 v[6:7], v[46:47], v[22:23], v[88:89] op_sel:[0,0,0] op_sel_hi:[0,1,1] neg_lo:[1,0,0] neg_hi:[1,0,0]
	v_pk_fma_f32 v[8:9], v[46:47], v[22:23], v[90:91] op_sel:[1,0,0] op_sel_hi:[1,1,1] neg_lo:[1,0,0] neg_hi:[1,0,0]
	s_waitcnt lgkmcnt(0)
	v_pk_mul_f32 v[22:23], v[2:3], v[60:61] op_sel:[0,0] op_sel_hi:[1,0]
	v_pk_mul_f32 v[24:25], v[2:3], v[52:53] op_sel:[0,0] op_sel_hi:[1,0]
	ds_read_b128 v[36:39], v20 offset:512
	v_pk_fma_f32 v[22:23], v[4:5], v[60:61], v[22:23] op_sel:[0,1,0] op_sel_hi:[1,1,1]
	v_pk_mul_f32 v[84:85], v[4:5], v[52:53] op_sel:[0,1] op_sel_hi:[1,1]
	ds_read_b128 v[40:43], v20 offset:8704
	v_pk_fma_f32 v[22:23], v[6:7], v[62:63], v[22:23] op_sel:[0,0,0] op_sel_hi:[1,0,1]
	v_pk_fma_f32 v[24:25], v[6:7], v[54:55], v[24:25] op_sel:[0,0,0] op_sel_hi:[1,0,1]
	ds_read_b64 v[56:57], v21 offset:41472
	v_pk_fma_f32 v[22:23], v[8:9], v[62:63], v[22:23] op_sel:[0,1,0] op_sel_hi:[1,1,1]
	v_pk_fma_f32 v[84:85], v[8:9], v[54:55], v[84:85] op_sel:[0,1,0] op_sel_hi:[1,1,1]
	ds_read_b128 v[48:51], v20 offset:25088
	v_pk_add_f32 v[24:25], v[24:25], v[84:85]
	ds_read_b128 v[44:47], v20 offset:16896
	ds_read_b128 v[52:55], v20 offset:33280
	v_add_f32_dpp v22, v22, v22 quad_perm:[1,0,3,2] row_mask:0xf bank_mask:0xf
	v_add_f32_dpp v23, v23, v23 quad_perm:[1,0,3,2] row_mask:0xf bank_mask:0xf
	v_pk_mul_f32 v[84:85], v[2:3], v[64:65] op_sel:[0,0] op_sel_hi:[1,0]
	v_pk_mul_f32 v[86:87], v[4:5], v[64:65] op_sel:[0,1] op_sel_hi:[1,1]
	v_add_f32_dpp v22, v22, v22 quad_perm:[2,3,0,1] row_mask:0xf bank_mask:0xf
	v_add_f32_dpp v23, v23, v23 quad_perm:[2,3,0,1] row_mask:0xf bank_mask:0xf
	v_pk_mul_f32 v[88:89], v[6:7], v[66:67] op_sel:[0,0] op_sel_hi:[1,0]
	v_pk_mul_f32 v[90:91], v[8:9], v[66:67] op_sel:[0,1] op_sel_hi:[1,1]
	v_add_f32_dpp v22, v22, v22 row_half_mirror row_mask:0xf bank_mask:0xf
	v_add_f32_dpp v23, v23, v23 row_half_mirror row_mask:0xf bank_mask:0xf
	v_pk_fma_f32 v[84:85], v[72:73], v[80:81], v[84:85] op_sel:[0,0,0] op_sel_hi:[0,1,1]
	v_pk_fma_f32 v[86:87], v[72:73], v[80:81], v[86:87] op_sel:[1,0,0] op_sel_hi:[1,1,1]
	v_add_f32_dpp v22, v22, v22 row_mirror row_mask:0xf bank_mask:0xf
	v_add_f32_dpp v23, v23, v23 row_mirror row_mask:0xf bank_mask:0xf
	v_pk_fma_f32 v[88:89], v[74:75], v[80:81], v[88:89] op_sel:[0,0,0] op_sel_hi:[0,1,1]
	v_pk_fma_f32 v[90:91], v[74:75], v[80:81], v[90:91] op_sel:[1,0,0] op_sel_hi:[1,1,1]
	v_pk_fma_f32 v[2:3], v[68:69], v[22:23], v[84:85] op_sel:[0,0,0] op_sel_hi:[0,1,1] neg_lo:[1,0,0] neg_hi:[1,0,0]
	v_pk_fma_f32 v[4:5], v[68:69], v[22:23], v[86:87] op_sel:[1,0,0] op_sel_hi:[1,1,1] neg_lo:[1,0,0] neg_hi:[1,0,0]
	v_pk_fma_f32 v[6:7], v[70:71], v[22:23], v[88:89] op_sel:[0,0,0] op_sel_hi:[0,1,1] neg_lo:[1,0,0] neg_hi:[1,0,0]
	v_pk_fma_f32 v[8:9], v[70:71], v[22:23], v[90:91] op_sel:[1,0,0] op_sel_hi:[1,1,1] neg_lo:[1,0,0] neg_hi:[1,0,0]
	s_waitcnt lgkmcnt(0)
	v_pk_mul_f32 v[22:23], v[2:3], v[36:37] op_sel:[0,0] op_sel_hi:[1,0]
	v_pk_mul_f32 v[26:27], v[2:3], v[76:77] op_sel:[0,0] op_sel_hi:[1,0]
	ds_read_b128 v[60:63], v20 offset:768
	v_pk_fma_f32 v[22:23], v[4:5], v[36:37], v[22:23] op_sel:[0,1,0] op_sel_hi:[1,1,1]
	v_pk_mul_f32 v[84:85], v[4:5], v[76:77] op_sel:[0,1] op_sel_hi:[1,1]
	ds_read_b128 v[64:67], v20 offset:8960
	v_pk_fma_f32 v[22:23], v[6:7], v[38:39], v[22:23] op_sel:[0,0,0] op_sel_hi:[1,0,1]
	v_pk_fma_f32 v[26:27], v[6:7], v[78:79], v[26:27] op_sel:[0,0,0] op_sel_hi:[1,0,1]
	ds_read_b64 v[80:81], v21 offset:41728
	v_pk_fma_f32 v[22:23], v[8:9], v[38:39], v[22:23] op_sel:[0,1,0] op_sel_hi:[1,1,1]
	v_pk_fma_f32 v[84:85], v[8:9], v[78:79], v[84:85] op_sel:[0,1,0] op_sel_hi:[1,1,1]
	ds_read_b128 v[72:75], v20 offset:25344
	v_pk_add_f32 v[26:27], v[26:27], v[84:85]
	ds_read_b128 v[68:71], v20 offset:17152
	ds_read_b128 v[76:79], v20 offset:33536
	v_add_f32_dpp v24, v24, v24 row_ror:12 row_mask:0xf bank_mask:0x5
	v_add_f32_dpp v25, v25, v25 row_ror:4 row_mask:0xf bank_mask:0xa
	v_add_f32_dpp v22, v22, v22 quad_perm:[1,0,3,2] row_mask:0xf bank_mask:0xf
	v_add_f32_dpp v23, v23, v23 quad_perm:[1,0,3,2] row_mask:0xf bank_mask:0xf
	v_pk_mul_f32 v[84:85], v[2:3], v[40:41] op_sel:[0,0] op_sel_hi:[1,0]
	v_pk_mul_f32 v[86:87], v[4:5], v[40:41] op_sel:[0,1] op_sel_hi:[1,1]
	v_mov_b32_dpp v24, v25 quad_perm:[0,1,2,3] row_mask:0xf bank_mask:0xa
	v_add_f32_dpp v22, v22, v22 quad_perm:[2,3,0,1] row_mask:0xf bank_mask:0xf
	v_add_f32_dpp v23, v23, v23 quad_perm:[2,3,0,1] row_mask:0xf bank_mask:0xf
	v_pk_mul_f32 v[88:89], v[6:7], v[42:43] op_sel:[0,0] op_sel_hi:[1,0]
	v_pk_mul_f32 v[90:91], v[8:9], v[42:43] op_sel:[0,1] op_sel_hi:[1,1]
	v_add_f32_dpp v24, v24, v24 row_ror:8 row_mask:0xf bank_mask:0xf
	v_add_f32_dpp v22, v22, v22 row_half_mirror row_mask:0xf bank_mask:0xf
	v_add_f32_dpp v23, v23, v23 row_half_mirror row_mask:0xf bank_mask:0xf
	v_pk_fma_f32 v[84:85], v[48:49], v[56:57], v[84:85] op_sel:[0,0,0] op_sel_hi:[0,1,1]
	v_pk_fma_f32 v[86:87], v[48:49], v[56:57], v[86:87] op_sel:[1,0,0] op_sel_hi:[1,1,1]
	v_add_f32_dpp v24, v24, v24 quad_perm:[1,0,3,2] row_mask:0xf bank_mask:0xf
	v_add_f32_dpp v22, v22, v22 row_mirror row_mask:0xf bank_mask:0xf
	v_add_f32_dpp v23, v23, v23 row_mirror row_mask:0xf bank_mask:0xf
	v_pk_fma_f32 v[88:89], v[50:51], v[56:57], v[88:89] op_sel:[0,0,0] op_sel_hi:[0,1,1]
	v_pk_fma_f32 v[90:91], v[50:51], v[56:57], v[90:91] op_sel:[1,0,0] op_sel_hi:[1,1,1]
	v_add_f32_dpp v24, v24, v24 quad_perm:[2,3,0,1] row_mask:0xf bank_mask:0xf
	v_cndmask_b32_e64 v30, 0, v24, s[0:1]
	v_pk_fma_f32 v[2:3], v[44:45], v[22:23], v[84:85] op_sel:[0,0,0] op_sel_hi:[0,1,1] neg_lo:[1,0,0] neg_hi:[1,0,0]
	v_pk_fma_f32 v[4:5], v[44:45], v[22:23], v[86:87] op_sel:[1,0,0] op_sel_hi:[1,1,1] neg_lo:[1,0,0] neg_hi:[1,0,0]
	v_pk_fma_f32 v[6:7], v[46:47], v[22:23], v[88:89] op_sel:[0,0,0] op_sel_hi:[0,1,1] neg_lo:[1,0,0] neg_hi:[1,0,0]
	v_pk_fma_f32 v[8:9], v[46:47], v[22:23], v[90:91] op_sel:[1,0,0] op_sel_hi:[1,1,1] neg_lo:[1,0,0] neg_hi:[1,0,0]
	s_waitcnt lgkmcnt(0)
	v_pk_mul_f32 v[22:23], v[2:3], v[60:61] op_sel:[0,0] op_sel_hi:[1,0]
	v_pk_mul_f32 v[24:25], v[2:3], v[52:53] op_sel:[0,0] op_sel_hi:[1,0]
	ds_read_b128 v[36:39], v20 offset:1024
	v_pk_fma_f32 v[22:23], v[4:5], v[60:61], v[22:23] op_sel:[0,1,0] op_sel_hi:[1,1,1]
	v_pk_mul_f32 v[84:85], v[4:5], v[52:53] op_sel:[0,1] op_sel_hi:[1,1]
	ds_read_b128 v[40:43], v20 offset:9216
	v_pk_fma_f32 v[22:23], v[6:7], v[62:63], v[22:23] op_sel:[0,0,0] op_sel_hi:[1,0,1]
	v_pk_fma_f32 v[24:25], v[6:7], v[54:55], v[24:25] op_sel:[0,0,0] op_sel_hi:[1,0,1]
	ds_read_b64 v[56:57], v21 offset:41984
	v_pk_fma_f32 v[22:23], v[8:9], v[62:63], v[22:23] op_sel:[0,1,0] op_sel_hi:[1,1,1]
	v_pk_fma_f32 v[84:85], v[8:9], v[54:55], v[84:85] op_sel:[0,1,0] op_sel_hi:[1,1,1]
	ds_read_b128 v[48:51], v20 offset:25600
	v_pk_add_f32 v[24:25], v[24:25], v[84:85]
	ds_read_b128 v[44:47], v20 offset:17408
	ds_read_b128 v[52:55], v20 offset:33792
	v_add_f32_dpp v26, v26, v26 row_ror:12 row_mask:0xf bank_mask:0x5
	v_add_f32_dpp v27, v27, v27 row_ror:4 row_mask:0xf bank_mask:0xa
	v_add_f32_dpp v22, v22, v22 quad_perm:[1,0,3,2] row_mask:0xf bank_mask:0xf
	v_add_f32_dpp v23, v23, v23 quad_perm:[1,0,3,2] row_mask:0xf bank_mask:0xf
	v_pk_mul_f32 v[84:85], v[2:3], v[64:65] op_sel:[0,0] op_sel_hi:[1,0]
	v_pk_mul_f32 v[86:87], v[4:5], v[64:65] op_sel:[0,1] op_sel_hi:[1,1]
	v_mov_b32_dpp v26, v27 quad_perm:[0,1,2,3] row_mask:0xf bank_mask:0xa
	v_add_f32_dpp v22, v22, v22 quad_perm:[2,3,0,1] row_mask:0xf bank_mask:0xf
	v_add_f32_dpp v23, v23, v23 quad_perm:[2,3,0,1] row_mask:0xf bank_mask:0xf
	v_pk_mul_f32 v[88:89], v[6:7], v[66:67] op_sel:[0,0] op_sel_hi:[1,0]
	v_pk_mul_f32 v[90:91], v[8:9], v[66:67] op_sel:[0,1] op_sel_hi:[1,1]
	v_add_f32_dpp v26, v26, v26 row_ror:8 row_mask:0xf bank_mask:0xf
	v_add_f32_dpp v22, v22, v22 row_half_mirror row_mask:0xf bank_mask:0xf
	v_add_f32_dpp v23, v23, v23 row_half_mirror row_mask:0xf bank_mask:0xf
	v_pk_fma_f32 v[84:85], v[72:73], v[80:81], v[84:85] op_sel:[0,0,0] op_sel_hi:[0,1,1]
	v_pk_fma_f32 v[86:87], v[72:73], v[80:81], v[86:87] op_sel:[1,0,0] op_sel_hi:[1,1,1]
	v_add_f32_dpp v26, v26, v26 quad_perm:[1,0,3,2] row_mask:0xf bank_mask:0xf
	v_add_f32_dpp v22, v22, v22 row_mirror row_mask:0xf bank_mask:0xf
	v_add_f32_dpp v23, v23, v23 row_mirror row_mask:0xf bank_mask:0xf
	v_pk_fma_f32 v[88:89], v[74:75], v[80:81], v[88:89] op_sel:[0,0,0] op_sel_hi:[0,1,1]
	v_pk_fma_f32 v[90:91], v[74:75], v[80:81], v[90:91] op_sel:[1,0,0] op_sel_hi:[1,1,1]
	v_add_f32_dpp v26, v26, v26 quad_perm:[2,3,0,1] row_mask:0xf bank_mask:0xf
	v_cndmask_b32_e64 v30, v30, v26, s[6:7]
	v_pk_fma_f32 v[2:3], v[68:69], v[22:23], v[84:85] op_sel:[0,0,0] op_sel_hi:[0,1,1] neg_lo:[1,0,0] neg_hi:[1,0,0]
	v_pk_fma_f32 v[4:5], v[68:69], v[22:23], v[86:87] op_sel:[1,0,0] op_sel_hi:[1,1,1] neg_lo:[1,0,0] neg_hi:[1,0,0]
	v_pk_fma_f32 v[6:7], v[70:71], v[22:23], v[88:89] op_sel:[0,0,0] op_sel_hi:[0,1,1] neg_lo:[1,0,0] neg_hi:[1,0,0]
	v_pk_fma_f32 v[8:9], v[70:71], v[22:23], v[90:91] op_sel:[1,0,0] op_sel_hi:[1,1,1] neg_lo:[1,0,0] neg_hi:[1,0,0]
	s_waitcnt lgkmcnt(0)
	v_pk_mul_f32 v[22:23], v[2:3], v[36:37] op_sel:[0,0] op_sel_hi:[1,0]
	v_pk_mul_f32 v[26:27], v[2:3], v[76:77] op_sel:[0,0] op_sel_hi:[1,0]
	ds_read_b128 v[60:63], v20 offset:1280
	v_pk_fma_f32 v[22:23], v[4:5], v[36:37], v[22:23] op_sel:[0,1,0] op_sel_hi:[1,1,1]
	v_pk_mul_f32 v[84:85], v[4:5], v[76:77] op_sel:[0,1] op_sel_hi:[1,1]
	ds_read_b128 v[64:67], v20 offset:9472
	v_pk_fma_f32 v[22:23], v[6:7], v[38:39], v[22:23] op_sel:[0,0,0] op_sel_hi:[1,0,1]
	v_pk_fma_f32 v[26:27], v[6:7], v[78:79], v[26:27] op_sel:[0,0,0] op_sel_hi:[1,0,1]
	ds_read_b64 v[80:81], v21 offset:42240
	v_pk_fma_f32 v[22:23], v[8:9], v[38:39], v[22:23] op_sel:[0,1,0] op_sel_hi:[1,1,1]
	v_pk_fma_f32 v[84:85], v[8:9], v[78:79], v[84:85] op_sel:[0,1,0] op_sel_hi:[1,1,1]
	ds_read_b128 v[72:75], v20 offset:25856
	v_pk_add_f32 v[26:27], v[26:27], v[84:85]
	ds_read_b128 v[68:71], v20 offset:17664
	ds_read_b128 v[76:79], v20 offset:34048
	v_add_f32_dpp v24, v24, v24 row_ror:12 row_mask:0xf bank_mask:0x5
	v_add_f32_dpp v25, v25, v25 row_ror:4 row_mask:0xf bank_mask:0xa
	v_add_f32_dpp v22, v22, v22 quad_perm:[1,0,3,2] row_mask:0xf bank_mask:0xf
	v_add_f32_dpp v23, v23, v23 quad_perm:[1,0,3,2] row_mask:0xf bank_mask:0xf
	v_pk_mul_f32 v[84:85], v[2:3], v[40:41] op_sel:[0,0] op_sel_hi:[1,0]
	v_pk_mul_f32 v[86:87], v[4:5], v[40:41] op_sel:[0,1] op_sel_hi:[1,1]
	v_mov_b32_dpp v24, v25 quad_perm:[0,1,2,3] row_mask:0xf bank_mask:0xa
	v_add_f32_dpp v22, v22, v22 quad_perm:[2,3,0,1] row_mask:0xf bank_mask:0xf
	v_add_f32_dpp v23, v23, v23 quad_perm:[2,3,0,1] row_mask:0xf bank_mask:0xf
	v_pk_mul_f32 v[88:89], v[6:7], v[42:43] op_sel:[0,0] op_sel_hi:[1,0]
	v_pk_mul_f32 v[90:91], v[8:9], v[42:43] op_sel:[0,1] op_sel_hi:[1,1]
	v_add_f32_dpp v24, v24, v24 row_ror:8 row_mask:0xf bank_mask:0xf
	v_add_f32_dpp v22, v22, v22 row_half_mirror row_mask:0xf bank_mask:0xf
	v_add_f32_dpp v23, v23, v23 row_half_mirror row_mask:0xf bank_mask:0xf
	v_pk_fma_f32 v[84:85], v[48:49], v[56:57], v[84:85] op_sel:[0,0,0] op_sel_hi:[0,1,1]
	v_pk_fma_f32 v[86:87], v[48:49], v[56:57], v[86:87] op_sel:[1,0,0] op_sel_hi:[1,1,1]
	v_add_f32_dpp v24, v24, v24 quad_perm:[1,0,3,2] row_mask:0xf bank_mask:0xf
	v_add_f32_dpp v22, v22, v22 row_mirror row_mask:0xf bank_mask:0xf
	v_add_f32_dpp v23, v23, v23 row_mirror row_mask:0xf bank_mask:0xf
	v_pk_fma_f32 v[88:89], v[50:51], v[56:57], v[88:89] op_sel:[0,0,0] op_sel_hi:[0,1,1]
	v_pk_fma_f32 v[90:91], v[50:51], v[56:57], v[90:91] op_sel:[1,0,0] op_sel_hi:[1,1,1]
	v_add_f32_dpp v24, v24, v24 quad_perm:[2,3,0,1] row_mask:0xf bank_mask:0xf
	v_cndmask_b32_e64 v30, v30, v24, s[8:9]
	v_pk_fma_f32 v[2:3], v[44:45], v[22:23], v[84:85] op_sel:[0,0,0] op_sel_hi:[0,1,1] neg_lo:[1,0,0] neg_hi:[1,0,0]
	v_pk_fma_f32 v[4:5], v[44:45], v[22:23], v[86:87] op_sel:[1,0,0] op_sel_hi:[1,1,1] neg_lo:[1,0,0] neg_hi:[1,0,0]
	v_pk_fma_f32 v[6:7], v[46:47], v[22:23], v[88:89] op_sel:[0,0,0] op_sel_hi:[0,1,1] neg_lo:[1,0,0] neg_hi:[1,0,0]
	v_pk_fma_f32 v[8:9], v[46:47], v[22:23], v[90:91] op_sel:[1,0,0] op_sel_hi:[1,1,1] neg_lo:[1,0,0] neg_hi:[1,0,0]
	s_waitcnt lgkmcnt(0)
	v_pk_mul_f32 v[22:23], v[2:3], v[60:61] op_sel:[0,0] op_sel_hi:[1,0]
	v_pk_mul_f32 v[24:25], v[2:3], v[52:53] op_sel:[0,0] op_sel_hi:[1,0]
	ds_read_b128 v[36:39], v20 offset:1536
	v_pk_fma_f32 v[22:23], v[4:5], v[60:61], v[22:23] op_sel:[0,1,0] op_sel_hi:[1,1,1]
	v_pk_mul_f32 v[84:85], v[4:5], v[52:53] op_sel:[0,1] op_sel_hi:[1,1]
	ds_read_b128 v[40:43], v20 offset:9728
	v_pk_fma_f32 v[22:23], v[6:7], v[62:63], v[22:23] op_sel:[0,0,0] op_sel_hi:[1,0,1]
	v_pk_fma_f32 v[24:25], v[6:7], v[54:55], v[24:25] op_sel:[0,0,0] op_sel_hi:[1,0,1]
	ds_read_b64 v[56:57], v21 offset:42496
	v_pk_fma_f32 v[22:23], v[8:9], v[62:63], v[22:23] op_sel:[0,1,0] op_sel_hi:[1,1,1]
	v_pk_fma_f32 v[84:85], v[8:9], v[54:55], v[84:85] op_sel:[0,1,0] op_sel_hi:[1,1,1]
	ds_read_b128 v[48:51], v20 offset:26112
	v_pk_add_f32 v[24:25], v[24:25], v[84:85]
	ds_read_b128 v[44:47], v20 offset:17920
	ds_read_b128 v[52:55], v20 offset:34304
	v_add_f32_dpp v26, v26, v26 row_ror:12 row_mask:0xf bank_mask:0x5
	v_add_f32_dpp v27, v27, v27 row_ror:4 row_mask:0xf bank_mask:0xa
	v_add_f32_dpp v22, v22, v22 quad_perm:[1,0,3,2] row_mask:0xf bank_mask:0xf
	v_add_f32_dpp v23, v23, v23 quad_perm:[1,0,3,2] row_mask:0xf bank_mask:0xf
	v_pk_mul_f32 v[84:85], v[2:3], v[64:65] op_sel:[0,0] op_sel_hi:[1,0]
	v_pk_mul_f32 v[86:87], v[4:5], v[64:65] op_sel:[0,1] op_sel_hi:[1,1]
	v_mov_b32_dpp v26, v27 quad_perm:[0,1,2,3] row_mask:0xf bank_mask:0xa
	v_add_f32_dpp v22, v22, v22 quad_perm:[2,3,0,1] row_mask:0xf bank_mask:0xf
	v_add_f32_dpp v23, v23, v23 quad_perm:[2,3,0,1] row_mask:0xf bank_mask:0xf
	v_pk_mul_f32 v[88:89], v[6:7], v[66:67] op_sel:[0,0] op_sel_hi:[1,0]
	v_pk_mul_f32 v[90:91], v[8:9], v[66:67] op_sel:[0,1] op_sel_hi:[1,1]
	v_add_f32_dpp v26, v26, v26 row_ror:8 row_mask:0xf bank_mask:0xf
	v_add_f32_dpp v22, v22, v22 row_half_mirror row_mask:0xf bank_mask:0xf
	v_add_f32_dpp v23, v23, v23 row_half_mirror row_mask:0xf bank_mask:0xf
	v_pk_fma_f32 v[84:85], v[72:73], v[80:81], v[84:85] op_sel:[0,0,0] op_sel_hi:[0,1,1]
	v_pk_fma_f32 v[86:87], v[72:73], v[80:81], v[86:87] op_sel:[1,0,0] op_sel_hi:[1,1,1]
	v_add_f32_dpp v26, v26, v26 quad_perm:[1,0,3,2] row_mask:0xf bank_mask:0xf
	v_add_f32_dpp v22, v22, v22 row_mirror row_mask:0xf bank_mask:0xf
	v_add_f32_dpp v23, v23, v23 row_mirror row_mask:0xf bank_mask:0xf
	v_pk_fma_f32 v[88:89], v[74:75], v[80:81], v[88:89] op_sel:[0,0,0] op_sel_hi:[0,1,1]
	v_pk_fma_f32 v[90:91], v[74:75], v[80:81], v[90:91] op_sel:[1,0,0] op_sel_hi:[1,1,1]
	v_add_f32_dpp v26, v26, v26 quad_perm:[2,3,0,1] row_mask:0xf bank_mask:0xf
	v_cndmask_b32_e64 v30, v30, v26, s[10:11]
	v_pk_fma_f32 v[2:3], v[68:69], v[22:23], v[84:85] op_sel:[0,0,0] op_sel_hi:[0,1,1] neg_lo:[1,0,0] neg_hi:[1,0,0]
	v_pk_fma_f32 v[4:5], v[68:69], v[22:23], v[86:87] op_sel:[1,0,0] op_sel_hi:[1,1,1] neg_lo:[1,0,0] neg_hi:[1,0,0]
	v_pk_fma_f32 v[6:7], v[70:71], v[22:23], v[88:89] op_sel:[0,0,0] op_sel_hi:[0,1,1] neg_lo:[1,0,0] neg_hi:[1,0,0]
	v_pk_fma_f32 v[8:9], v[70:71], v[22:23], v[90:91] op_sel:[1,0,0] op_sel_hi:[1,1,1] neg_lo:[1,0,0] neg_hi:[1,0,0]
	s_waitcnt lgkmcnt(0)
	v_pk_mul_f32 v[22:23], v[2:3], v[36:37] op_sel:[0,0] op_sel_hi:[1,0]
	v_pk_mul_f32 v[26:27], v[2:3], v[76:77] op_sel:[0,0] op_sel_hi:[1,0]
	ds_read_b128 v[60:63], v20 offset:1792
	v_pk_fma_f32 v[22:23], v[4:5], v[36:37], v[22:23] op_sel:[0,1,0] op_sel_hi:[1,1,1]
	v_pk_mul_f32 v[84:85], v[4:5], v[76:77] op_sel:[0,1] op_sel_hi:[1,1]
	ds_read_b128 v[64:67], v20 offset:9984
	v_pk_fma_f32 v[22:23], v[6:7], v[38:39], v[22:23] op_sel:[0,0,0] op_sel_hi:[1,0,1]
	v_pk_fma_f32 v[26:27], v[6:7], v[78:79], v[26:27] op_sel:[0,0,0] op_sel_hi:[1,0,1]
	ds_read_b64 v[80:81], v21 offset:42752
	v_pk_fma_f32 v[22:23], v[8:9], v[38:39], v[22:23] op_sel:[0,1,0] op_sel_hi:[1,1,1]
	v_pk_fma_f32 v[84:85], v[8:9], v[78:79], v[84:85] op_sel:[0,1,0] op_sel_hi:[1,1,1]
	ds_read_b128 v[72:75], v20 offset:26368
	v_pk_add_f32 v[26:27], v[26:27], v[84:85]
	ds_read_b128 v[68:71], v20 offset:18176
	ds_read_b128 v[76:79], v20 offset:34560
	v_add_f32_dpp v24, v24, v24 row_ror:12 row_mask:0xf bank_mask:0x5
	v_add_f32_dpp v25, v25, v25 row_ror:4 row_mask:0xf bank_mask:0xa
	v_add_f32_dpp v22, v22, v22 quad_perm:[1,0,3,2] row_mask:0xf bank_mask:0xf
	v_add_f32_dpp v23, v23, v23 quad_perm:[1,0,3,2] row_mask:0xf bank_mask:0xf
	v_pk_mul_f32 v[84:85], v[2:3], v[40:41] op_sel:[0,0] op_sel_hi:[1,0]
	v_pk_mul_f32 v[86:87], v[4:5], v[40:41] op_sel:[0,1] op_sel_hi:[1,1]
	v_mov_b32_dpp v24, v25 quad_perm:[0,1,2,3] row_mask:0xf bank_mask:0xa
	v_add_f32_dpp v22, v22, v22 quad_perm:[2,3,0,1] row_mask:0xf bank_mask:0xf
	v_add_f32_dpp v23, v23, v23 quad_perm:[2,3,0,1] row_mask:0xf bank_mask:0xf
	v_pk_mul_f32 v[88:89], v[6:7], v[42:43] op_sel:[0,0] op_sel_hi:[1,0]
	v_pk_mul_f32 v[90:91], v[8:9], v[42:43] op_sel:[0,1] op_sel_hi:[1,1]
	v_add_f32_dpp v24, v24, v24 row_ror:8 row_mask:0xf bank_mask:0xf
	v_add_f32_dpp v22, v22, v22 row_half_mirror row_mask:0xf bank_mask:0xf
	v_add_f32_dpp v23, v23, v23 row_half_mirror row_mask:0xf bank_mask:0xf
	v_pk_fma_f32 v[84:85], v[48:49], v[56:57], v[84:85] op_sel:[0,0,0] op_sel_hi:[0,1,1]
	v_pk_fma_f32 v[86:87], v[48:49], v[56:57], v[86:87] op_sel:[1,0,0] op_sel_hi:[1,1,1]
	v_add_f32_dpp v24, v24, v24 quad_perm:[1,0,3,2] row_mask:0xf bank_mask:0xf
	v_add_f32_dpp v22, v22, v22 row_mirror row_mask:0xf bank_mask:0xf
	v_add_f32_dpp v23, v23, v23 row_mirror row_mask:0xf bank_mask:0xf
	v_pk_fma_f32 v[88:89], v[50:51], v[56:57], v[88:89] op_sel:[0,0,0] op_sel_hi:[0,1,1]
	v_pk_fma_f32 v[90:91], v[50:51], v[56:57], v[90:91] op_sel:[1,0,0] op_sel_hi:[1,1,1]
	v_add_f32_dpp v24, v24, v24 quad_perm:[2,3,0,1] row_mask:0xf bank_mask:0xf
	v_cndmask_b32_e64 v30, v30, v24, s[12:13]
	v_pk_fma_f32 v[2:3], v[44:45], v[22:23], v[84:85] op_sel:[0,0,0] op_sel_hi:[0,1,1] neg_lo:[1,0,0] neg_hi:[1,0,0]
	v_pk_fma_f32 v[4:5], v[44:45], v[22:23], v[86:87] op_sel:[1,0,0] op_sel_hi:[1,1,1] neg_lo:[1,0,0] neg_hi:[1,0,0]
	v_pk_fma_f32 v[6:7], v[46:47], v[22:23], v[88:89] op_sel:[0,0,0] op_sel_hi:[0,1,1] neg_lo:[1,0,0] neg_hi:[1,0,0]
	v_pk_fma_f32 v[8:9], v[46:47], v[22:23], v[90:91] op_sel:[1,0,0] op_sel_hi:[1,1,1] neg_lo:[1,0,0] neg_hi:[1,0,0]
	s_waitcnt lgkmcnt(0)
	v_pk_mul_f32 v[22:23], v[2:3], v[60:61] op_sel:[0,0] op_sel_hi:[1,0]
	v_pk_mul_f32 v[24:25], v[2:3], v[52:53] op_sel:[0,0] op_sel_hi:[1,0]
	ds_read_b128 v[36:39], v20 offset:2048
	v_pk_fma_f32 v[22:23], v[4:5], v[60:61], v[22:23] op_sel:[0,1,0] op_sel_hi:[1,1,1]
	v_pk_mul_f32 v[84:85], v[4:5], v[52:53] op_sel:[0,1] op_sel_hi:[1,1]
	ds_read_b128 v[40:43], v20 offset:10240
	v_pk_fma_f32 v[22:23], v[6:7], v[62:63], v[22:23] op_sel:[0,0,0] op_sel_hi:[1,0,1]
	v_pk_fma_f32 v[24:25], v[6:7], v[54:55], v[24:25] op_sel:[0,0,0] op_sel_hi:[1,0,1]
	ds_read_b64 v[56:57], v21 offset:43008
	v_pk_fma_f32 v[22:23], v[8:9], v[62:63], v[22:23] op_sel:[0,1,0] op_sel_hi:[1,1,1]
	v_pk_fma_f32 v[84:85], v[8:9], v[54:55], v[84:85] op_sel:[0,1,0] op_sel_hi:[1,1,1]
	ds_read_b128 v[48:51], v20 offset:26624
	v_pk_add_f32 v[24:25], v[24:25], v[84:85]
	ds_read_b128 v[44:47], v20 offset:18432
	ds_read_b128 v[52:55], v20 offset:34816
	v_add_f32_dpp v26, v26, v26 row_ror:12 row_mask:0xf bank_mask:0x5
	v_add_f32_dpp v27, v27, v27 row_ror:4 row_mask:0xf bank_mask:0xa
	v_add_f32_dpp v22, v22, v22 quad_perm:[1,0,3,2] row_mask:0xf bank_mask:0xf
	v_add_f32_dpp v23, v23, v23 quad_perm:[1,0,3,2] row_mask:0xf bank_mask:0xf
	v_pk_mul_f32 v[84:85], v[2:3], v[64:65] op_sel:[0,0] op_sel_hi:[1,0]
	v_pk_mul_f32 v[86:87], v[4:5], v[64:65] op_sel:[0,1] op_sel_hi:[1,1]
	v_mov_b32_dpp v26, v27 quad_perm:[0,1,2,3] row_mask:0xf bank_mask:0xa
	v_add_f32_dpp v22, v22, v22 quad_perm:[2,3,0,1] row_mask:0xf bank_mask:0xf
	v_add_f32_dpp v23, v23, v23 quad_perm:[2,3,0,1] row_mask:0xf bank_mask:0xf
	v_pk_mul_f32 v[88:89], v[6:7], v[66:67] op_sel:[0,0] op_sel_hi:[1,0]
	v_pk_mul_f32 v[90:91], v[8:9], v[66:67] op_sel:[0,1] op_sel_hi:[1,1]
	v_add_f32_dpp v26, v26, v26 row_ror:8 row_mask:0xf bank_mask:0xf
	v_add_f32_dpp v22, v22, v22 row_half_mirror row_mask:0xf bank_mask:0xf
	v_add_f32_dpp v23, v23, v23 row_half_mirror row_mask:0xf bank_mask:0xf
	v_pk_fma_f32 v[84:85], v[72:73], v[80:81], v[84:85] op_sel:[0,0,0] op_sel_hi:[0,1,1]
	v_pk_fma_f32 v[86:87], v[72:73], v[80:81], v[86:87] op_sel:[1,0,0] op_sel_hi:[1,1,1]
	v_add_f32_dpp v26, v26, v26 quad_perm:[1,0,3,2] row_mask:0xf bank_mask:0xf
	v_add_f32_dpp v22, v22, v22 row_mirror row_mask:0xf bank_mask:0xf
	v_add_f32_dpp v23, v23, v23 row_mirror row_mask:0xf bank_mask:0xf
	v_pk_fma_f32 v[88:89], v[74:75], v[80:81], v[88:89] op_sel:[0,0,0] op_sel_hi:[0,1,1]
	v_pk_fma_f32 v[90:91], v[74:75], v[80:81], v[90:91] op_sel:[1,0,0] op_sel_hi:[1,1,1]
	v_add_f32_dpp v26, v26, v26 quad_perm:[2,3,0,1] row_mask:0xf bank_mask:0xf
	v_cndmask_b32_e64 v30, v30, v26, s[14:15]
	v_pk_fma_f32 v[2:3], v[68:69], v[22:23], v[84:85] op_sel:[0,0,0] op_sel_hi:[0,1,1] neg_lo:[1,0,0] neg_hi:[1,0,0]
	v_pk_fma_f32 v[4:5], v[68:69], v[22:23], v[86:87] op_sel:[1,0,0] op_sel_hi:[1,1,1] neg_lo:[1,0,0] neg_hi:[1,0,0]
	v_pk_fma_f32 v[6:7], v[70:71], v[22:23], v[88:89] op_sel:[0,0,0] op_sel_hi:[0,1,1] neg_lo:[1,0,0] neg_hi:[1,0,0]
	v_pk_fma_f32 v[8:9], v[70:71], v[22:23], v[90:91] op_sel:[1,0,0] op_sel_hi:[1,1,1] neg_lo:[1,0,0] neg_hi:[1,0,0]
	s_waitcnt lgkmcnt(0)
	v_pk_mul_f32 v[22:23], v[2:3], v[36:37] op_sel:[0,0] op_sel_hi:[1,0]
	v_pk_mul_f32 v[26:27], v[2:3], v[76:77] op_sel:[0,0] op_sel_hi:[1,0]
	ds_read_b128 v[60:63], v20 offset:2304
	v_pk_fma_f32 v[22:23], v[4:5], v[36:37], v[22:23] op_sel:[0,1,0] op_sel_hi:[1,1,1]
	v_pk_mul_f32 v[84:85], v[4:5], v[76:77] op_sel:[0,1] op_sel_hi:[1,1]
	ds_read_b128 v[64:67], v20 offset:10496
	v_pk_fma_f32 v[22:23], v[6:7], v[38:39], v[22:23] op_sel:[0,0,0] op_sel_hi:[1,0,1]
	v_pk_fma_f32 v[26:27], v[6:7], v[78:79], v[26:27] op_sel:[0,0,0] op_sel_hi:[1,0,1]
	ds_read_b64 v[80:81], v21 offset:43264
	v_pk_fma_f32 v[22:23], v[8:9], v[38:39], v[22:23] op_sel:[0,1,0] op_sel_hi:[1,1,1]
	v_pk_fma_f32 v[84:85], v[8:9], v[78:79], v[84:85] op_sel:[0,1,0] op_sel_hi:[1,1,1]
	ds_read_b128 v[72:75], v20 offset:26880
	v_pk_add_f32 v[26:27], v[26:27], v[84:85]
	ds_read_b128 v[68:71], v20 offset:18688
	ds_read_b128 v[76:79], v20 offset:35072
	v_add_f32_dpp v24, v24, v24 row_ror:12 row_mask:0xf bank_mask:0x5
	v_add_f32_dpp v25, v25, v25 row_ror:4 row_mask:0xf bank_mask:0xa
	v_add_f32_dpp v22, v22, v22 quad_perm:[1,0,3,2] row_mask:0xf bank_mask:0xf
	v_add_f32_dpp v23, v23, v23 quad_perm:[1,0,3,2] row_mask:0xf bank_mask:0xf
	v_pk_mul_f32 v[84:85], v[2:3], v[40:41] op_sel:[0,0] op_sel_hi:[1,0]
	v_pk_mul_f32 v[86:87], v[4:5], v[40:41] op_sel:[0,1] op_sel_hi:[1,1]
	v_mov_b32_dpp v24, v25 quad_perm:[0,1,2,3] row_mask:0xf bank_mask:0xa
	v_add_f32_dpp v22, v22, v22 quad_perm:[2,3,0,1] row_mask:0xf bank_mask:0xf
	v_add_f32_dpp v23, v23, v23 quad_perm:[2,3,0,1] row_mask:0xf bank_mask:0xf
	v_pk_mul_f32 v[88:89], v[6:7], v[42:43] op_sel:[0,0] op_sel_hi:[1,0]
	v_pk_mul_f32 v[90:91], v[8:9], v[42:43] op_sel:[0,1] op_sel_hi:[1,1]
	v_add_f32_dpp v24, v24, v24 row_ror:8 row_mask:0xf bank_mask:0xf
	v_add_f32_dpp v22, v22, v22 row_half_mirror row_mask:0xf bank_mask:0xf
	v_add_f32_dpp v23, v23, v23 row_half_mirror row_mask:0xf bank_mask:0xf
	v_pk_fma_f32 v[84:85], v[48:49], v[56:57], v[84:85] op_sel:[0,0,0] op_sel_hi:[0,1,1]
	v_pk_fma_f32 v[86:87], v[48:49], v[56:57], v[86:87] op_sel:[1,0,0] op_sel_hi:[1,1,1]
	v_add_f32_dpp v24, v24, v24 quad_perm:[1,0,3,2] row_mask:0xf bank_mask:0xf
	v_add_f32_dpp v22, v22, v22 row_mirror row_mask:0xf bank_mask:0xf
	v_add_f32_dpp v23, v23, v23 row_mirror row_mask:0xf bank_mask:0xf
	v_pk_fma_f32 v[88:89], v[50:51], v[56:57], v[88:89] op_sel:[0,0,0] op_sel_hi:[0,1,1]
	v_pk_fma_f32 v[90:91], v[50:51], v[56:57], v[90:91] op_sel:[1,0,0] op_sel_hi:[1,1,1]
	v_add_f32_dpp v24, v24, v24 quad_perm:[2,3,0,1] row_mask:0xf bank_mask:0xf
	v_cndmask_b32_e64 v30, v30, v24, s[16:17]
	v_pk_fma_f32 v[2:3], v[44:45], v[22:23], v[84:85] op_sel:[0,0,0] op_sel_hi:[0,1,1] neg_lo:[1,0,0] neg_hi:[1,0,0]
	v_pk_fma_f32 v[4:5], v[44:45], v[22:23], v[86:87] op_sel:[1,0,0] op_sel_hi:[1,1,1] neg_lo:[1,0,0] neg_hi:[1,0,0]
	v_pk_fma_f32 v[6:7], v[46:47], v[22:23], v[88:89] op_sel:[0,0,0] op_sel_hi:[0,1,1] neg_lo:[1,0,0] neg_hi:[1,0,0]
	v_pk_fma_f32 v[8:9], v[46:47], v[22:23], v[90:91] op_sel:[1,0,0] op_sel_hi:[1,1,1] neg_lo:[1,0,0] neg_hi:[1,0,0]
	s_waitcnt lgkmcnt(0)
	v_pk_mul_f32 v[22:23], v[2:3], v[60:61] op_sel:[0,0] op_sel_hi:[1,0]
	v_pk_mul_f32 v[24:25], v[2:3], v[52:53] op_sel:[0,0] op_sel_hi:[1,0]
	ds_read_b128 v[36:39], v20 offset:2560
	v_pk_fma_f32 v[22:23], v[4:5], v[60:61], v[22:23] op_sel:[0,1,0] op_sel_hi:[1,1,1]
	v_pk_mul_f32 v[84:85], v[4:5], v[52:53] op_sel:[0,1] op_sel_hi:[1,1]
	ds_read_b128 v[40:43], v20 offset:10752
	v_pk_fma_f32 v[22:23], v[6:7], v[62:63], v[22:23] op_sel:[0,0,0] op_sel_hi:[1,0,1]
	v_pk_fma_f32 v[24:25], v[6:7], v[54:55], v[24:25] op_sel:[0,0,0] op_sel_hi:[1,0,1]
	ds_read_b64 v[56:57], v21 offset:43520
	v_pk_fma_f32 v[22:23], v[8:9], v[62:63], v[22:23] op_sel:[0,1,0] op_sel_hi:[1,1,1]
	v_pk_fma_f32 v[84:85], v[8:9], v[54:55], v[84:85] op_sel:[0,1,0] op_sel_hi:[1,1,1]
	ds_read_b128 v[48:51], v20 offset:27136
	v_pk_add_f32 v[24:25], v[24:25], v[84:85]
	ds_read_b128 v[44:47], v20 offset:18944
	ds_read_b128 v[52:55], v20 offset:35328
	v_add_f32_dpp v26, v26, v26 row_ror:12 row_mask:0xf bank_mask:0x5
	v_add_f32_dpp v27, v27, v27 row_ror:4 row_mask:0xf bank_mask:0xa
	v_add_f32_dpp v22, v22, v22 quad_perm:[1,0,3,2] row_mask:0xf bank_mask:0xf
	v_add_f32_dpp v23, v23, v23 quad_perm:[1,0,3,2] row_mask:0xf bank_mask:0xf
	v_pk_mul_f32 v[84:85], v[2:3], v[64:65] op_sel:[0,0] op_sel_hi:[1,0]
	v_pk_mul_f32 v[86:87], v[4:5], v[64:65] op_sel:[0,1] op_sel_hi:[1,1]
	v_mov_b32_dpp v26, v27 quad_perm:[0,1,2,3] row_mask:0xf bank_mask:0xa
	v_add_f32_dpp v22, v22, v22 quad_perm:[2,3,0,1] row_mask:0xf bank_mask:0xf
	v_add_f32_dpp v23, v23, v23 quad_perm:[2,3,0,1] row_mask:0xf bank_mask:0xf
	v_pk_mul_f32 v[88:89], v[6:7], v[66:67] op_sel:[0,0] op_sel_hi:[1,0]
	v_pk_mul_f32 v[90:91], v[8:9], v[66:67] op_sel:[0,1] op_sel_hi:[1,1]
	v_add_f32_dpp v26, v26, v26 row_ror:8 row_mask:0xf bank_mask:0xf
	v_add_f32_dpp v22, v22, v22 row_half_mirror row_mask:0xf bank_mask:0xf
	v_add_f32_dpp v23, v23, v23 row_half_mirror row_mask:0xf bank_mask:0xf
	v_pk_fma_f32 v[84:85], v[72:73], v[80:81], v[84:85] op_sel:[0,0,0] op_sel_hi:[0,1,1]
	v_pk_fma_f32 v[86:87], v[72:73], v[80:81], v[86:87] op_sel:[1,0,0] op_sel_hi:[1,1,1]
	v_add_f32_dpp v26, v26, v26 quad_perm:[1,0,3,2] row_mask:0xf bank_mask:0xf
	v_add_f32_dpp v22, v22, v22 row_mirror row_mask:0xf bank_mask:0xf
	v_add_f32_dpp v23, v23, v23 row_mirror row_mask:0xf bank_mask:0xf
	v_pk_fma_f32 v[88:89], v[74:75], v[80:81], v[88:89] op_sel:[0,0,0] op_sel_hi:[0,1,1]
	v_pk_fma_f32 v[90:91], v[74:75], v[80:81], v[90:91] op_sel:[1,0,0] op_sel_hi:[1,1,1]
	v_add_f32_dpp v26, v26, v26 quad_perm:[2,3,0,1] row_mask:0xf bank_mask:0xf
	v_cndmask_b32_e32 v30, v30, v26, vcc
	v_pk_fma_f32 v[2:3], v[68:69], v[22:23], v[84:85] op_sel:[0,0,0] op_sel_hi:[0,1,1] neg_lo:[1,0,0] neg_hi:[1,0,0]
	v_pk_fma_f32 v[4:5], v[68:69], v[22:23], v[86:87] op_sel:[1,0,0] op_sel_hi:[1,1,1] neg_lo:[1,0,0] neg_hi:[1,0,0]
	v_pk_fma_f32 v[6:7], v[70:71], v[22:23], v[88:89] op_sel:[0,0,0] op_sel_hi:[0,1,1] neg_lo:[1,0,0] neg_hi:[1,0,0]
	v_pk_fma_f32 v[8:9], v[70:71], v[22:23], v[90:91] op_sel:[1,0,0] op_sel_hi:[1,1,1] neg_lo:[1,0,0] neg_hi:[1,0,0]
	s_waitcnt lgkmcnt(0)
	v_pk_mul_f32 v[22:23], v[2:3], v[36:37] op_sel:[0,0] op_sel_hi:[1,0]
	v_pk_mul_f32 v[26:27], v[2:3], v[76:77] op_sel:[0,0] op_sel_hi:[1,0]
	ds_read_b128 v[60:63], v20 offset:2816
	v_pk_fma_f32 v[22:23], v[4:5], v[36:37], v[22:23] op_sel:[0,1,0] op_sel_hi:[1,1,1]
	v_pk_mul_f32 v[84:85], v[4:5], v[76:77] op_sel:[0,1] op_sel_hi:[1,1]
	ds_read_b128 v[64:67], v20 offset:11008
	v_pk_fma_f32 v[22:23], v[6:7], v[38:39], v[22:23] op_sel:[0,0,0] op_sel_hi:[1,0,1]
	v_pk_fma_f32 v[26:27], v[6:7], v[78:79], v[26:27] op_sel:[0,0,0] op_sel_hi:[1,0,1]
	ds_read_b64 v[80:81], v21 offset:43776
	v_pk_fma_f32 v[22:23], v[8:9], v[38:39], v[22:23] op_sel:[0,1,0] op_sel_hi:[1,1,1]
	v_pk_fma_f32 v[84:85], v[8:9], v[78:79], v[84:85] op_sel:[0,1,0] op_sel_hi:[1,1,1]
	ds_read_b128 v[72:75], v20 offset:27392
	v_pk_add_f32 v[26:27], v[26:27], v[84:85]
	ds_read_b128 v[68:71], v20 offset:19200
	ds_read_b128 v[76:79], v20 offset:35584
	v_add_f32_dpp v24, v24, v24 row_ror:12 row_mask:0xf bank_mask:0x5
	v_add_f32_dpp v25, v25, v25 row_ror:4 row_mask:0xf bank_mask:0xa
	v_add_f32_dpp v22, v22, v22 quad_perm:[1,0,3,2] row_mask:0xf bank_mask:0xf
	v_add_f32_dpp v23, v23, v23 quad_perm:[1,0,3,2] row_mask:0xf bank_mask:0xf
	v_pk_mul_f32 v[84:85], v[2:3], v[40:41] op_sel:[0,0] op_sel_hi:[1,0]
	v_pk_mul_f32 v[86:87], v[4:5], v[40:41] op_sel:[0,1] op_sel_hi:[1,1]
	v_mov_b32_dpp v24, v25 quad_perm:[0,1,2,3] row_mask:0xf bank_mask:0xa
	v_add_f32_dpp v22, v22, v22 quad_perm:[2,3,0,1] row_mask:0xf bank_mask:0xf
	v_add_f32_dpp v23, v23, v23 quad_perm:[2,3,0,1] row_mask:0xf bank_mask:0xf
	v_pk_mul_f32 v[88:89], v[6:7], v[42:43] op_sel:[0,0] op_sel_hi:[1,0]
	v_pk_mul_f32 v[90:91], v[8:9], v[42:43] op_sel:[0,1] op_sel_hi:[1,1]
	v_add_f32_dpp v24, v24, v24 row_ror:8 row_mask:0xf bank_mask:0xf
	v_add_f32_dpp v22, v22, v22 row_half_mirror row_mask:0xf bank_mask:0xf
	v_add_f32_dpp v23, v23, v23 row_half_mirror row_mask:0xf bank_mask:0xf
	v_pk_fma_f32 v[84:85], v[48:49], v[56:57], v[84:85] op_sel:[0,0,0] op_sel_hi:[0,1,1]
	v_pk_fma_f32 v[86:87], v[48:49], v[56:57], v[86:87] op_sel:[1,0,0] op_sel_hi:[1,1,1]
	v_add_f32_dpp v24, v24, v24 quad_perm:[1,0,3,2] row_mask:0xf bank_mask:0xf
	v_add_f32_dpp v22, v22, v22 row_mirror row_mask:0xf bank_mask:0xf
	v_add_f32_dpp v23, v23, v23 row_mirror row_mask:0xf bank_mask:0xf
	v_pk_fma_f32 v[88:89], v[50:51], v[56:57], v[88:89] op_sel:[0,0,0] op_sel_hi:[0,1,1]
	v_pk_fma_f32 v[90:91], v[50:51], v[56:57], v[90:91] op_sel:[1,0,0] op_sel_hi:[1,1,1]
	v_add_f32_dpp v24, v24, v24 quad_perm:[2,3,0,1] row_mask:0xf bank_mask:0xf
	v_cndmask_b32_e64 v31, 0, v24, s[0:1]
	v_pk_fma_f32 v[2:3], v[44:45], v[22:23], v[84:85] op_sel:[0,0,0] op_sel_hi:[0,1,1] neg_lo:[1,0,0] neg_hi:[1,0,0]
	v_pk_fma_f32 v[4:5], v[44:45], v[22:23], v[86:87] op_sel:[1,0,0] op_sel_hi:[1,1,1] neg_lo:[1,0,0] neg_hi:[1,0,0]
	v_pk_fma_f32 v[6:7], v[46:47], v[22:23], v[88:89] op_sel:[0,0,0] op_sel_hi:[0,1,1] neg_lo:[1,0,0] neg_hi:[1,0,0]
	v_pk_fma_f32 v[8:9], v[46:47], v[22:23], v[90:91] op_sel:[1,0,0] op_sel_hi:[1,1,1] neg_lo:[1,0,0] neg_hi:[1,0,0]
	s_waitcnt lgkmcnt(0)
	v_pk_mul_f32 v[22:23], v[2:3], v[60:61] op_sel:[0,0] op_sel_hi:[1,0]
	v_pk_mul_f32 v[24:25], v[2:3], v[52:53] op_sel:[0,0] op_sel_hi:[1,0]
	ds_read_b128 v[36:39], v20 offset:3072
	v_pk_fma_f32 v[22:23], v[4:5], v[60:61], v[22:23] op_sel:[0,1,0] op_sel_hi:[1,1,1]
	v_pk_mul_f32 v[84:85], v[4:5], v[52:53] op_sel:[0,1] op_sel_hi:[1,1]
	ds_read_b128 v[40:43], v20 offset:11264
	v_pk_fma_f32 v[22:23], v[6:7], v[62:63], v[22:23] op_sel:[0,0,0] op_sel_hi:[1,0,1]
	v_pk_fma_f32 v[24:25], v[6:7], v[54:55], v[24:25] op_sel:[0,0,0] op_sel_hi:[1,0,1]
	ds_read_b64 v[56:57], v21 offset:44032
	v_pk_fma_f32 v[22:23], v[8:9], v[62:63], v[22:23] op_sel:[0,1,0] op_sel_hi:[1,1,1]
	v_pk_fma_f32 v[84:85], v[8:9], v[54:55], v[84:85] op_sel:[0,1,0] op_sel_hi:[1,1,1]
	ds_read_b128 v[48:51], v20 offset:27648
	v_pk_add_f32 v[24:25], v[24:25], v[84:85]
	ds_read_b128 v[44:47], v20 offset:19456
	ds_read_b128 v[52:55], v20 offset:35840
	v_add_f32_dpp v26, v26, v26 row_ror:12 row_mask:0xf bank_mask:0x5
	v_add_f32_dpp v27, v27, v27 row_ror:4 row_mask:0xf bank_mask:0xa
	v_add_f32_dpp v22, v22, v22 quad_perm:[1,0,3,2] row_mask:0xf bank_mask:0xf
	v_add_f32_dpp v23, v23, v23 quad_perm:[1,0,3,2] row_mask:0xf bank_mask:0xf
	v_pk_mul_f32 v[84:85], v[2:3], v[64:65] op_sel:[0,0] op_sel_hi:[1,0]
	v_pk_mul_f32 v[86:87], v[4:5], v[64:65] op_sel:[0,1] op_sel_hi:[1,1]
	v_mov_b32_dpp v26, v27 quad_perm:[0,1,2,3] row_mask:0xf bank_mask:0xa
	v_add_f32_dpp v22, v22, v22 quad_perm:[2,3,0,1] row_mask:0xf bank_mask:0xf
	v_add_f32_dpp v23, v23, v23 quad_perm:[2,3,0,1] row_mask:0xf bank_mask:0xf
	v_pk_mul_f32 v[88:89], v[6:7], v[66:67] op_sel:[0,0] op_sel_hi:[1,0]
	v_pk_mul_f32 v[90:91], v[8:9], v[66:67] op_sel:[0,1] op_sel_hi:[1,1]
	v_add_f32_dpp v26, v26, v26 row_ror:8 row_mask:0xf bank_mask:0xf
	v_add_f32_dpp v22, v22, v22 row_half_mirror row_mask:0xf bank_mask:0xf
	v_add_f32_dpp v23, v23, v23 row_half_mirror row_mask:0xf bank_mask:0xf
	v_pk_fma_f32 v[84:85], v[72:73], v[80:81], v[84:85] op_sel:[0,0,0] op_sel_hi:[0,1,1]
	v_pk_fma_f32 v[86:87], v[72:73], v[80:81], v[86:87] op_sel:[1,0,0] op_sel_hi:[1,1,1]
	v_add_f32_dpp v26, v26, v26 quad_perm:[1,0,3,2] row_mask:0xf bank_mask:0xf
	v_add_f32_dpp v22, v22, v22 row_mirror row_mask:0xf bank_mask:0xf
	v_add_f32_dpp v23, v23, v23 row_mirror row_mask:0xf bank_mask:0xf
	v_pk_fma_f32 v[88:89], v[74:75], v[80:81], v[88:89] op_sel:[0,0,0] op_sel_hi:[0,1,1]
	v_pk_fma_f32 v[90:91], v[74:75], v[80:81], v[90:91] op_sel:[1,0,0] op_sel_hi:[1,1,1]
	v_add_f32_dpp v26, v26, v26 quad_perm:[2,3,0,1] row_mask:0xf bank_mask:0xf
	v_cndmask_b32_e64 v31, v31, v26, s[6:7]
	v_pk_fma_f32 v[2:3], v[68:69], v[22:23], v[84:85] op_sel:[0,0,0] op_sel_hi:[0,1,1] neg_lo:[1,0,0] neg_hi:[1,0,0]
	v_pk_fma_f32 v[4:5], v[68:69], v[22:23], v[86:87] op_sel:[1,0,0] op_sel_hi:[1,1,1] neg_lo:[1,0,0] neg_hi:[1,0,0]
	v_pk_fma_f32 v[6:7], v[70:71], v[22:23], v[88:89] op_sel:[0,0,0] op_sel_hi:[0,1,1] neg_lo:[1,0,0] neg_hi:[1,0,0]
	v_pk_fma_f32 v[8:9], v[70:71], v[22:23], v[90:91] op_sel:[1,0,0] op_sel_hi:[1,1,1] neg_lo:[1,0,0] neg_hi:[1,0,0]
	s_waitcnt lgkmcnt(0)
	v_pk_mul_f32 v[22:23], v[2:3], v[36:37] op_sel:[0,0] op_sel_hi:[1,0]
	v_pk_mul_f32 v[26:27], v[2:3], v[76:77] op_sel:[0,0] op_sel_hi:[1,0]
	ds_read_b128 v[60:63], v20 offset:3328
	v_pk_fma_f32 v[22:23], v[4:5], v[36:37], v[22:23] op_sel:[0,1,0] op_sel_hi:[1,1,1]
	v_pk_mul_f32 v[84:85], v[4:5], v[76:77] op_sel:[0,1] op_sel_hi:[1,1]
	ds_read_b128 v[64:67], v20 offset:11520
	v_pk_fma_f32 v[22:23], v[6:7], v[38:39], v[22:23] op_sel:[0,0,0] op_sel_hi:[1,0,1]
	v_pk_fma_f32 v[26:27], v[6:7], v[78:79], v[26:27] op_sel:[0,0,0] op_sel_hi:[1,0,1]
	ds_read_b64 v[80:81], v21 offset:44288
	v_pk_fma_f32 v[22:23], v[8:9], v[38:39], v[22:23] op_sel:[0,1,0] op_sel_hi:[1,1,1]
	v_pk_fma_f32 v[84:85], v[8:9], v[78:79], v[84:85] op_sel:[0,1,0] op_sel_hi:[1,1,1]
	ds_read_b128 v[72:75], v20 offset:27904
	v_pk_add_f32 v[26:27], v[26:27], v[84:85]
	ds_read_b128 v[68:71], v20 offset:19712
	ds_read_b128 v[76:79], v20 offset:36096
	v_add_f32_dpp v24, v24, v24 row_ror:12 row_mask:0xf bank_mask:0x5
	v_add_f32_dpp v25, v25, v25 row_ror:4 row_mask:0xf bank_mask:0xa
	v_add_f32_dpp v22, v22, v22 quad_perm:[1,0,3,2] row_mask:0xf bank_mask:0xf
	v_add_f32_dpp v23, v23, v23 quad_perm:[1,0,3,2] row_mask:0xf bank_mask:0xf
	v_pk_mul_f32 v[84:85], v[2:3], v[40:41] op_sel:[0,0] op_sel_hi:[1,0]
	v_pk_mul_f32 v[86:87], v[4:5], v[40:41] op_sel:[0,1] op_sel_hi:[1,1]
	v_mov_b32_dpp v24, v25 quad_perm:[0,1,2,3] row_mask:0xf bank_mask:0xa
	v_add_f32_dpp v22, v22, v22 quad_perm:[2,3,0,1] row_mask:0xf bank_mask:0xf
	v_add_f32_dpp v23, v23, v23 quad_perm:[2,3,0,1] row_mask:0xf bank_mask:0xf
	v_pk_mul_f32 v[88:89], v[6:7], v[42:43] op_sel:[0,0] op_sel_hi:[1,0]
	v_pk_mul_f32 v[90:91], v[8:9], v[42:43] op_sel:[0,1] op_sel_hi:[1,1]
	v_add_f32_dpp v24, v24, v24 row_ror:8 row_mask:0xf bank_mask:0xf
	v_add_f32_dpp v22, v22, v22 row_half_mirror row_mask:0xf bank_mask:0xf
	v_add_f32_dpp v23, v23, v23 row_half_mirror row_mask:0xf bank_mask:0xf
	v_pk_fma_f32 v[84:85], v[48:49], v[56:57], v[84:85] op_sel:[0,0,0] op_sel_hi:[0,1,1]
	v_pk_fma_f32 v[86:87], v[48:49], v[56:57], v[86:87] op_sel:[1,0,0] op_sel_hi:[1,1,1]
	v_add_f32_dpp v24, v24, v24 quad_perm:[1,0,3,2] row_mask:0xf bank_mask:0xf
	v_add_f32_dpp v22, v22, v22 row_mirror row_mask:0xf bank_mask:0xf
	v_add_f32_dpp v23, v23, v23 row_mirror row_mask:0xf bank_mask:0xf
	v_pk_fma_f32 v[88:89], v[50:51], v[56:57], v[88:89] op_sel:[0,0,0] op_sel_hi:[0,1,1]
	v_pk_fma_f32 v[90:91], v[50:51], v[56:57], v[90:91] op_sel:[1,0,0] op_sel_hi:[1,1,1]
	v_add_f32_dpp v24, v24, v24 quad_perm:[2,3,0,1] row_mask:0xf bank_mask:0xf
	v_cndmask_b32_e64 v31, v31, v24, s[8:9]
	v_pk_fma_f32 v[2:3], v[44:45], v[22:23], v[84:85] op_sel:[0,0,0] op_sel_hi:[0,1,1] neg_lo:[1,0,0] neg_hi:[1,0,0]
	v_pk_fma_f32 v[4:5], v[44:45], v[22:23], v[86:87] op_sel:[1,0,0] op_sel_hi:[1,1,1] neg_lo:[1,0,0] neg_hi:[1,0,0]
	v_pk_fma_f32 v[6:7], v[46:47], v[22:23], v[88:89] op_sel:[0,0,0] op_sel_hi:[0,1,1] neg_lo:[1,0,0] neg_hi:[1,0,0]
	v_pk_fma_f32 v[8:9], v[46:47], v[22:23], v[90:91] op_sel:[1,0,0] op_sel_hi:[1,1,1] neg_lo:[1,0,0] neg_hi:[1,0,0]
	s_waitcnt lgkmcnt(0)
	v_pk_mul_f32 v[22:23], v[2:3], v[60:61] op_sel:[0,0] op_sel_hi:[1,0]
	v_pk_mul_f32 v[24:25], v[2:3], v[52:53] op_sel:[0,0] op_sel_hi:[1,0]
	ds_read_b128 v[36:39], v20 offset:3584
	v_pk_fma_f32 v[22:23], v[4:5], v[60:61], v[22:23] op_sel:[0,1,0] op_sel_hi:[1,1,1]
	v_pk_mul_f32 v[84:85], v[4:5], v[52:53] op_sel:[0,1] op_sel_hi:[1,1]
	ds_read_b128 v[40:43], v20 offset:11776
	v_pk_fma_f32 v[22:23], v[6:7], v[62:63], v[22:23] op_sel:[0,0,0] op_sel_hi:[1,0,1]
	v_pk_fma_f32 v[24:25], v[6:7], v[54:55], v[24:25] op_sel:[0,0,0] op_sel_hi:[1,0,1]
	ds_read_b64 v[56:57], v21 offset:44544
	v_pk_fma_f32 v[22:23], v[8:9], v[62:63], v[22:23] op_sel:[0,1,0] op_sel_hi:[1,1,1]
	v_pk_fma_f32 v[84:85], v[8:9], v[54:55], v[84:85] op_sel:[0,1,0] op_sel_hi:[1,1,1]
	ds_read_b128 v[48:51], v20 offset:28160
	v_pk_add_f32 v[24:25], v[24:25], v[84:85]
	ds_read_b128 v[44:47], v20 offset:19968
	ds_read_b128 v[52:55], v20 offset:36352
	v_add_f32_dpp v26, v26, v26 row_ror:12 row_mask:0xf bank_mask:0x5
	v_add_f32_dpp v27, v27, v27 row_ror:4 row_mask:0xf bank_mask:0xa
	v_add_f32_dpp v22, v22, v22 quad_perm:[1,0,3,2] row_mask:0xf bank_mask:0xf
	v_add_f32_dpp v23, v23, v23 quad_perm:[1,0,3,2] row_mask:0xf bank_mask:0xf
	v_pk_mul_f32 v[84:85], v[2:3], v[64:65] op_sel:[0,0] op_sel_hi:[1,0]
	v_pk_mul_f32 v[86:87], v[4:5], v[64:65] op_sel:[0,1] op_sel_hi:[1,1]
	v_mov_b32_dpp v26, v27 quad_perm:[0,1,2,3] row_mask:0xf bank_mask:0xa
	v_add_f32_dpp v22, v22, v22 quad_perm:[2,3,0,1] row_mask:0xf bank_mask:0xf
	v_add_f32_dpp v23, v23, v23 quad_perm:[2,3,0,1] row_mask:0xf bank_mask:0xf
	v_pk_mul_f32 v[88:89], v[6:7], v[66:67] op_sel:[0,0] op_sel_hi:[1,0]
	v_pk_mul_f32 v[90:91], v[8:9], v[66:67] op_sel:[0,1] op_sel_hi:[1,1]
	v_add_f32_dpp v26, v26, v26 row_ror:8 row_mask:0xf bank_mask:0xf
	v_add_f32_dpp v22, v22, v22 row_half_mirror row_mask:0xf bank_mask:0xf
	v_add_f32_dpp v23, v23, v23 row_half_mirror row_mask:0xf bank_mask:0xf
	v_pk_fma_f32 v[84:85], v[72:73], v[80:81], v[84:85] op_sel:[0,0,0] op_sel_hi:[0,1,1]
	v_pk_fma_f32 v[86:87], v[72:73], v[80:81], v[86:87] op_sel:[1,0,0] op_sel_hi:[1,1,1]
	v_add_f32_dpp v26, v26, v26 quad_perm:[1,0,3,2] row_mask:0xf bank_mask:0xf
	v_add_f32_dpp v22, v22, v22 row_mirror row_mask:0xf bank_mask:0xf
	v_add_f32_dpp v23, v23, v23 row_mirror row_mask:0xf bank_mask:0xf
	v_pk_fma_f32 v[88:89], v[74:75], v[80:81], v[88:89] op_sel:[0,0,0] op_sel_hi:[0,1,1]
	v_pk_fma_f32 v[90:91], v[74:75], v[80:81], v[90:91] op_sel:[1,0,0] op_sel_hi:[1,1,1]
	v_add_f32_dpp v26, v26, v26 quad_perm:[2,3,0,1] row_mask:0xf bank_mask:0xf
	v_cndmask_b32_e64 v31, v31, v26, s[10:11]
	v_pk_fma_f32 v[2:3], v[68:69], v[22:23], v[84:85] op_sel:[0,0,0] op_sel_hi:[0,1,1] neg_lo:[1,0,0] neg_hi:[1,0,0]
	v_pk_fma_f32 v[4:5], v[68:69], v[22:23], v[86:87] op_sel:[1,0,0] op_sel_hi:[1,1,1] neg_lo:[1,0,0] neg_hi:[1,0,0]
	v_pk_fma_f32 v[6:7], v[70:71], v[22:23], v[88:89] op_sel:[0,0,0] op_sel_hi:[0,1,1] neg_lo:[1,0,0] neg_hi:[1,0,0]
	v_pk_fma_f32 v[8:9], v[70:71], v[22:23], v[90:91] op_sel:[1,0,0] op_sel_hi:[1,1,1] neg_lo:[1,0,0] neg_hi:[1,0,0]
	s_waitcnt lgkmcnt(0)
	v_pk_mul_f32 v[22:23], v[2:3], v[36:37] op_sel:[0,0] op_sel_hi:[1,0]
	v_pk_mul_f32 v[26:27], v[2:3], v[76:77] op_sel:[0,0] op_sel_hi:[1,0]
	ds_read_b128 v[60:63], v20 offset:3840
	v_pk_fma_f32 v[22:23], v[4:5], v[36:37], v[22:23] op_sel:[0,1,0] op_sel_hi:[1,1,1]
	v_pk_mul_f32 v[84:85], v[4:5], v[76:77] op_sel:[0,1] op_sel_hi:[1,1]
	ds_read_b128 v[64:67], v20 offset:12032
	v_pk_fma_f32 v[22:23], v[6:7], v[38:39], v[22:23] op_sel:[0,0,0] op_sel_hi:[1,0,1]
	v_pk_fma_f32 v[26:27], v[6:7], v[78:79], v[26:27] op_sel:[0,0,0] op_sel_hi:[1,0,1]
	ds_read_b64 v[80:81], v21 offset:44800
	v_pk_fma_f32 v[22:23], v[8:9], v[38:39], v[22:23] op_sel:[0,1,0] op_sel_hi:[1,1,1]
	v_pk_fma_f32 v[84:85], v[8:9], v[78:79], v[84:85] op_sel:[0,1,0] op_sel_hi:[1,1,1]
	ds_read_b128 v[72:75], v20 offset:28416
	v_pk_add_f32 v[26:27], v[26:27], v[84:85]
	ds_read_b128 v[68:71], v20 offset:20224
	ds_read_b128 v[76:79], v20 offset:36608
	v_add_f32_dpp v24, v24, v24 row_ror:12 row_mask:0xf bank_mask:0x5
	v_add_f32_dpp v25, v25, v25 row_ror:4 row_mask:0xf bank_mask:0xa
	v_add_f32_dpp v22, v22, v22 quad_perm:[1,0,3,2] row_mask:0xf bank_mask:0xf
	v_add_f32_dpp v23, v23, v23 quad_perm:[1,0,3,2] row_mask:0xf bank_mask:0xf
	v_pk_mul_f32 v[84:85], v[2:3], v[40:41] op_sel:[0,0] op_sel_hi:[1,0]
	v_pk_mul_f32 v[86:87], v[4:5], v[40:41] op_sel:[0,1] op_sel_hi:[1,1]
	v_mov_b32_dpp v24, v25 quad_perm:[0,1,2,3] row_mask:0xf bank_mask:0xa
	v_add_f32_dpp v22, v22, v22 quad_perm:[2,3,0,1] row_mask:0xf bank_mask:0xf
	v_add_f32_dpp v23, v23, v23 quad_perm:[2,3,0,1] row_mask:0xf bank_mask:0xf
	v_pk_mul_f32 v[88:89], v[6:7], v[42:43] op_sel:[0,0] op_sel_hi:[1,0]
	v_pk_mul_f32 v[90:91], v[8:9], v[42:43] op_sel:[0,1] op_sel_hi:[1,1]
	v_add_f32_dpp v24, v24, v24 row_ror:8 row_mask:0xf bank_mask:0xf
	v_add_f32_dpp v22, v22, v22 row_half_mirror row_mask:0xf bank_mask:0xf
	v_add_f32_dpp v23, v23, v23 row_half_mirror row_mask:0xf bank_mask:0xf
	v_pk_fma_f32 v[84:85], v[48:49], v[56:57], v[84:85] op_sel:[0,0,0] op_sel_hi:[0,1,1]
	v_pk_fma_f32 v[86:87], v[48:49], v[56:57], v[86:87] op_sel:[1,0,0] op_sel_hi:[1,1,1]
	v_add_f32_dpp v24, v24, v24 quad_perm:[1,0,3,2] row_mask:0xf bank_mask:0xf
	v_add_f32_dpp v22, v22, v22 row_mirror row_mask:0xf bank_mask:0xf
	v_add_f32_dpp v23, v23, v23 row_mirror row_mask:0xf bank_mask:0xf
	v_pk_fma_f32 v[88:89], v[50:51], v[56:57], v[88:89] op_sel:[0,0,0] op_sel_hi:[0,1,1]
	v_pk_fma_f32 v[90:91], v[50:51], v[56:57], v[90:91] op_sel:[1,0,0] op_sel_hi:[1,1,1]
	v_add_f32_dpp v24, v24, v24 quad_perm:[2,3,0,1] row_mask:0xf bank_mask:0xf
	v_cndmask_b32_e64 v31, v31, v24, s[12:13]
	v_pk_fma_f32 v[2:3], v[44:45], v[22:23], v[84:85] op_sel:[0,0,0] op_sel_hi:[0,1,1] neg_lo:[1,0,0] neg_hi:[1,0,0]
	v_pk_fma_f32 v[4:5], v[44:45], v[22:23], v[86:87] op_sel:[1,0,0] op_sel_hi:[1,1,1] neg_lo:[1,0,0] neg_hi:[1,0,0]
	v_pk_fma_f32 v[6:7], v[46:47], v[22:23], v[88:89] op_sel:[0,0,0] op_sel_hi:[0,1,1] neg_lo:[1,0,0] neg_hi:[1,0,0]
	v_pk_fma_f32 v[8:9], v[46:47], v[22:23], v[90:91] op_sel:[1,0,0] op_sel_hi:[1,1,1] neg_lo:[1,0,0] neg_hi:[1,0,0]
	s_waitcnt lgkmcnt(0)
	v_pk_mul_f32 v[22:23], v[2:3], v[60:61] op_sel:[0,0] op_sel_hi:[1,0]
	v_pk_mul_f32 v[24:25], v[2:3], v[52:53] op_sel:[0,0] op_sel_hi:[1,0]
	ds_read_b128 v[36:39], v20 offset:4096
	v_pk_fma_f32 v[22:23], v[4:5], v[60:61], v[22:23] op_sel:[0,1,0] op_sel_hi:[1,1,1]
	v_pk_mul_f32 v[84:85], v[4:5], v[52:53] op_sel:[0,1] op_sel_hi:[1,1]
	ds_read_b128 v[40:43], v20 offset:12288
	v_pk_fma_f32 v[22:23], v[6:7], v[62:63], v[22:23] op_sel:[0,0,0] op_sel_hi:[1,0,1]
	v_pk_fma_f32 v[24:25], v[6:7], v[54:55], v[24:25] op_sel:[0,0,0] op_sel_hi:[1,0,1]
	ds_read_b64 v[56:57], v21 offset:45056
	v_pk_fma_f32 v[22:23], v[8:9], v[62:63], v[22:23] op_sel:[0,1,0] op_sel_hi:[1,1,1]
	v_pk_fma_f32 v[84:85], v[8:9], v[54:55], v[84:85] op_sel:[0,1,0] op_sel_hi:[1,1,1]
	ds_read_b128 v[48:51], v20 offset:28672
	v_pk_add_f32 v[24:25], v[24:25], v[84:85]
	ds_read_b128 v[44:47], v20 offset:20480
	ds_read_b128 v[52:55], v20 offset:36864
	v_add_f32_dpp v26, v26, v26 row_ror:12 row_mask:0xf bank_mask:0x5
	v_add_f32_dpp v27, v27, v27 row_ror:4 row_mask:0xf bank_mask:0xa
	v_add_f32_dpp v22, v22, v22 quad_perm:[1,0,3,2] row_mask:0xf bank_mask:0xf
	v_add_f32_dpp v23, v23, v23 quad_perm:[1,0,3,2] row_mask:0xf bank_mask:0xf
	v_pk_mul_f32 v[84:85], v[2:3], v[64:65] op_sel:[0,0] op_sel_hi:[1,0]
	v_pk_mul_f32 v[86:87], v[4:5], v[64:65] op_sel:[0,1] op_sel_hi:[1,1]
	v_mov_b32_dpp v26, v27 quad_perm:[0,1,2,3] row_mask:0xf bank_mask:0xa
	v_add_f32_dpp v22, v22, v22 quad_perm:[2,3,0,1] row_mask:0xf bank_mask:0xf
	v_add_f32_dpp v23, v23, v23 quad_perm:[2,3,0,1] row_mask:0xf bank_mask:0xf
	v_pk_mul_f32 v[88:89], v[6:7], v[66:67] op_sel:[0,0] op_sel_hi:[1,0]
	v_pk_mul_f32 v[90:91], v[8:9], v[66:67] op_sel:[0,1] op_sel_hi:[1,1]
	v_add_f32_dpp v26, v26, v26 row_ror:8 row_mask:0xf bank_mask:0xf
	v_add_f32_dpp v22, v22, v22 row_half_mirror row_mask:0xf bank_mask:0xf
	v_add_f32_dpp v23, v23, v23 row_half_mirror row_mask:0xf bank_mask:0xf
	v_pk_fma_f32 v[84:85], v[72:73], v[80:81], v[84:85] op_sel:[0,0,0] op_sel_hi:[0,1,1]
	v_pk_fma_f32 v[86:87], v[72:73], v[80:81], v[86:87] op_sel:[1,0,0] op_sel_hi:[1,1,1]
	v_add_f32_dpp v26, v26, v26 quad_perm:[1,0,3,2] row_mask:0xf bank_mask:0xf
	v_add_f32_dpp v22, v22, v22 row_mirror row_mask:0xf bank_mask:0xf
	v_add_f32_dpp v23, v23, v23 row_mirror row_mask:0xf bank_mask:0xf
	v_pk_fma_f32 v[88:89], v[74:75], v[80:81], v[88:89] op_sel:[0,0,0] op_sel_hi:[0,1,1]
	v_pk_fma_f32 v[90:91], v[74:75], v[80:81], v[90:91] op_sel:[1,0,0] op_sel_hi:[1,1,1]
	v_add_f32_dpp v26, v26, v26 quad_perm:[2,3,0,1] row_mask:0xf bank_mask:0xf
	v_cndmask_b32_e64 v31, v31, v26, s[14:15]
	v_pk_fma_f32 v[2:3], v[68:69], v[22:23], v[84:85] op_sel:[0,0,0] op_sel_hi:[0,1,1] neg_lo:[1,0,0] neg_hi:[1,0,0]
	v_pk_fma_f32 v[4:5], v[68:69], v[22:23], v[86:87] op_sel:[1,0,0] op_sel_hi:[1,1,1] neg_lo:[1,0,0] neg_hi:[1,0,0]
	v_pk_fma_f32 v[6:7], v[70:71], v[22:23], v[88:89] op_sel:[0,0,0] op_sel_hi:[0,1,1] neg_lo:[1,0,0] neg_hi:[1,0,0]
	v_pk_fma_f32 v[8:9], v[70:71], v[22:23], v[90:91] op_sel:[1,0,0] op_sel_hi:[1,1,1] neg_lo:[1,0,0] neg_hi:[1,0,0]
	s_waitcnt lgkmcnt(0)
	v_pk_mul_f32 v[22:23], v[2:3], v[36:37] op_sel:[0,0] op_sel_hi:[1,0]
	v_pk_mul_f32 v[26:27], v[2:3], v[76:77] op_sel:[0,0] op_sel_hi:[1,0]
	ds_read_b128 v[60:63], v20 offset:4352
	v_pk_fma_f32 v[22:23], v[4:5], v[36:37], v[22:23] op_sel:[0,1,0] op_sel_hi:[1,1,1]
	v_pk_mul_f32 v[84:85], v[4:5], v[76:77] op_sel:[0,1] op_sel_hi:[1,1]
	ds_read_b128 v[64:67], v20 offset:12544
	v_pk_fma_f32 v[22:23], v[6:7], v[38:39], v[22:23] op_sel:[0,0,0] op_sel_hi:[1,0,1]
	v_pk_fma_f32 v[26:27], v[6:7], v[78:79], v[26:27] op_sel:[0,0,0] op_sel_hi:[1,0,1]
	ds_read_b64 v[80:81], v21 offset:45312
	v_pk_fma_f32 v[22:23], v[8:9], v[38:39], v[22:23] op_sel:[0,1,0] op_sel_hi:[1,1,1]
	v_pk_fma_f32 v[84:85], v[8:9], v[78:79], v[84:85] op_sel:[0,1,0] op_sel_hi:[1,1,1]
	ds_read_b128 v[72:75], v20 offset:28928
	v_pk_add_f32 v[26:27], v[26:27], v[84:85]
	ds_read_b128 v[68:71], v20 offset:20736
	ds_read_b128 v[76:79], v20 offset:37120
	v_add_f32_dpp v24, v24, v24 row_ror:12 row_mask:0xf bank_mask:0x5
	v_add_f32_dpp v25, v25, v25 row_ror:4 row_mask:0xf bank_mask:0xa
	v_add_f32_dpp v22, v22, v22 quad_perm:[1,0,3,2] row_mask:0xf bank_mask:0xf
	v_add_f32_dpp v23, v23, v23 quad_perm:[1,0,3,2] row_mask:0xf bank_mask:0xf
	v_pk_mul_f32 v[84:85], v[2:3], v[40:41] op_sel:[0,0] op_sel_hi:[1,0]
	v_pk_mul_f32 v[86:87], v[4:5], v[40:41] op_sel:[0,1] op_sel_hi:[1,1]
	v_mov_b32_dpp v24, v25 quad_perm:[0,1,2,3] row_mask:0xf bank_mask:0xa
	v_add_f32_dpp v22, v22, v22 quad_perm:[2,3,0,1] row_mask:0xf bank_mask:0xf
	v_add_f32_dpp v23, v23, v23 quad_perm:[2,3,0,1] row_mask:0xf bank_mask:0xf
	v_pk_mul_f32 v[88:89], v[6:7], v[42:43] op_sel:[0,0] op_sel_hi:[1,0]
	v_pk_mul_f32 v[90:91], v[8:9], v[42:43] op_sel:[0,1] op_sel_hi:[1,1]
	v_add_f32_dpp v24, v24, v24 row_ror:8 row_mask:0xf bank_mask:0xf
	v_add_f32_dpp v22, v22, v22 row_half_mirror row_mask:0xf bank_mask:0xf
	v_add_f32_dpp v23, v23, v23 row_half_mirror row_mask:0xf bank_mask:0xf
	v_pk_fma_f32 v[84:85], v[48:49], v[56:57], v[84:85] op_sel:[0,0,0] op_sel_hi:[0,1,1]
	v_pk_fma_f32 v[86:87], v[48:49], v[56:57], v[86:87] op_sel:[1,0,0] op_sel_hi:[1,1,1]
	v_add_f32_dpp v24, v24, v24 quad_perm:[1,0,3,2] row_mask:0xf bank_mask:0xf
	v_add_f32_dpp v22, v22, v22 row_mirror row_mask:0xf bank_mask:0xf
	v_add_f32_dpp v23, v23, v23 row_mirror row_mask:0xf bank_mask:0xf
	v_pk_fma_f32 v[88:89], v[50:51], v[56:57], v[88:89] op_sel:[0,0,0] op_sel_hi:[0,1,1]
	v_pk_fma_f32 v[90:91], v[50:51], v[56:57], v[90:91] op_sel:[1,0,0] op_sel_hi:[1,1,1]
	v_add_f32_dpp v24, v24, v24 quad_perm:[2,3,0,1] row_mask:0xf bank_mask:0xf
	v_cndmask_b32_e64 v31, v31, v24, s[16:17]
	v_pk_fma_f32 v[2:3], v[44:45], v[22:23], v[84:85] op_sel:[0,0,0] op_sel_hi:[0,1,1] neg_lo:[1,0,0] neg_hi:[1,0,0]
	v_pk_fma_f32 v[4:5], v[44:45], v[22:23], v[86:87] op_sel:[1,0,0] op_sel_hi:[1,1,1] neg_lo:[1,0,0] neg_hi:[1,0,0]
	v_pk_fma_f32 v[6:7], v[46:47], v[22:23], v[88:89] op_sel:[0,0,0] op_sel_hi:[0,1,1] neg_lo:[1,0,0] neg_hi:[1,0,0]
	v_pk_fma_f32 v[8:9], v[46:47], v[22:23], v[90:91] op_sel:[1,0,0] op_sel_hi:[1,1,1] neg_lo:[1,0,0] neg_hi:[1,0,0]
	s_waitcnt lgkmcnt(0)
	v_pk_mul_f32 v[22:23], v[2:3], v[60:61] op_sel:[0,0] op_sel_hi:[1,0]
	v_pk_mul_f32 v[24:25], v[2:3], v[52:53] op_sel:[0,0] op_sel_hi:[1,0]
	ds_read_b128 v[36:39], v20 offset:4608
	v_pk_fma_f32 v[22:23], v[4:5], v[60:61], v[22:23] op_sel:[0,1,0] op_sel_hi:[1,1,1]
	v_pk_mul_f32 v[84:85], v[4:5], v[52:53] op_sel:[0,1] op_sel_hi:[1,1]
	ds_read_b128 v[40:43], v20 offset:12800
	v_pk_fma_f32 v[22:23], v[6:7], v[62:63], v[22:23] op_sel:[0,0,0] op_sel_hi:[1,0,1]
	v_pk_fma_f32 v[24:25], v[6:7], v[54:55], v[24:25] op_sel:[0,0,0] op_sel_hi:[1,0,1]
	ds_read_b64 v[56:57], v21 offset:45568
	v_pk_fma_f32 v[22:23], v[8:9], v[62:63], v[22:23] op_sel:[0,1,0] op_sel_hi:[1,1,1]
	v_pk_fma_f32 v[84:85], v[8:9], v[54:55], v[84:85] op_sel:[0,1,0] op_sel_hi:[1,1,1]
	ds_read_b128 v[48:51], v20 offset:29184
	v_pk_add_f32 v[24:25], v[24:25], v[84:85]
	ds_read_b128 v[44:47], v20 offset:20992
	ds_read_b128 v[52:55], v20 offset:37376
	v_add_f32_dpp v26, v26, v26 row_ror:12 row_mask:0xf bank_mask:0x5
	v_add_f32_dpp v27, v27, v27 row_ror:4 row_mask:0xf bank_mask:0xa
	v_add_f32_dpp v22, v22, v22 quad_perm:[1,0,3,2] row_mask:0xf bank_mask:0xf
	v_add_f32_dpp v23, v23, v23 quad_perm:[1,0,3,2] row_mask:0xf bank_mask:0xf
	v_pk_mul_f32 v[84:85], v[2:3], v[64:65] op_sel:[0,0] op_sel_hi:[1,0]
	v_pk_mul_f32 v[86:87], v[4:5], v[64:65] op_sel:[0,1] op_sel_hi:[1,1]
	v_mov_b32_dpp v26, v27 quad_perm:[0,1,2,3] row_mask:0xf bank_mask:0xa
	v_add_f32_dpp v22, v22, v22 quad_perm:[2,3,0,1] row_mask:0xf bank_mask:0xf
	v_add_f32_dpp v23, v23, v23 quad_perm:[2,3,0,1] row_mask:0xf bank_mask:0xf
	v_pk_mul_f32 v[88:89], v[6:7], v[66:67] op_sel:[0,0] op_sel_hi:[1,0]
	v_pk_mul_f32 v[90:91], v[8:9], v[66:67] op_sel:[0,1] op_sel_hi:[1,1]
	v_add_f32_dpp v26, v26, v26 row_ror:8 row_mask:0xf bank_mask:0xf
	v_add_f32_dpp v22, v22, v22 row_half_mirror row_mask:0xf bank_mask:0xf
	v_add_f32_dpp v23, v23, v23 row_half_mirror row_mask:0xf bank_mask:0xf
	v_pk_fma_f32 v[84:85], v[72:73], v[80:81], v[84:85] op_sel:[0,0,0] op_sel_hi:[0,1,1]
	v_pk_fma_f32 v[86:87], v[72:73], v[80:81], v[86:87] op_sel:[1,0,0] op_sel_hi:[1,1,1]
	v_add_f32_dpp v26, v26, v26 quad_perm:[1,0,3,2] row_mask:0xf bank_mask:0xf
	v_add_f32_dpp v22, v22, v22 row_mirror row_mask:0xf bank_mask:0xf
	v_add_f32_dpp v23, v23, v23 row_mirror row_mask:0xf bank_mask:0xf
	v_pk_fma_f32 v[88:89], v[74:75], v[80:81], v[88:89] op_sel:[0,0,0] op_sel_hi:[0,1,1]
	v_pk_fma_f32 v[90:91], v[74:75], v[80:81], v[90:91] op_sel:[1,0,0] op_sel_hi:[1,1,1]
	v_add_f32_dpp v26, v26, v26 quad_perm:[2,3,0,1] row_mask:0xf bank_mask:0xf
	v_cndmask_b32_e32 v31, v31, v26, vcc
	v_pk_fma_f32 v[2:3], v[68:69], v[22:23], v[84:85] op_sel:[0,0,0] op_sel_hi:[0,1,1] neg_lo:[1,0,0] neg_hi:[1,0,0]
	v_pk_fma_f32 v[4:5], v[68:69], v[22:23], v[86:87] op_sel:[1,0,0] op_sel_hi:[1,1,1] neg_lo:[1,0,0] neg_hi:[1,0,0]
	v_pk_fma_f32 v[6:7], v[70:71], v[22:23], v[88:89] op_sel:[0,0,0] op_sel_hi:[0,1,1] neg_lo:[1,0,0] neg_hi:[1,0,0]
	v_pk_fma_f32 v[8:9], v[70:71], v[22:23], v[90:91] op_sel:[1,0,0] op_sel_hi:[1,1,1] neg_lo:[1,0,0] neg_hi:[1,0,0]
	s_waitcnt lgkmcnt(0)
	v_pk_mul_f32 v[22:23], v[2:3], v[36:37] op_sel:[0,0] op_sel_hi:[1,0]
	v_pk_mul_f32 v[26:27], v[2:3], v[76:77] op_sel:[0,0] op_sel_hi:[1,0]
	ds_read_b128 v[60:63], v20 offset:4864
	v_pk_fma_f32 v[22:23], v[4:5], v[36:37], v[22:23] op_sel:[0,1,0] op_sel_hi:[1,1,1]
	v_pk_mul_f32 v[84:85], v[4:5], v[76:77] op_sel:[0,1] op_sel_hi:[1,1]
	ds_read_b128 v[64:67], v20 offset:13056
	v_pk_fma_f32 v[22:23], v[6:7], v[38:39], v[22:23] op_sel:[0,0,0] op_sel_hi:[1,0,1]
	v_pk_fma_f32 v[26:27], v[6:7], v[78:79], v[26:27] op_sel:[0,0,0] op_sel_hi:[1,0,1]
	ds_read_b64 v[80:81], v21 offset:45824
	v_pk_fma_f32 v[22:23], v[8:9], v[38:39], v[22:23] op_sel:[0,1,0] op_sel_hi:[1,1,1]
	v_pk_fma_f32 v[84:85], v[8:9], v[78:79], v[84:85] op_sel:[0,1,0] op_sel_hi:[1,1,1]
	ds_read_b128 v[72:75], v20 offset:29440
	v_pk_add_f32 v[26:27], v[26:27], v[84:85]
	ds_read_b128 v[68:71], v20 offset:21248
	ds_read_b128 v[76:79], v20 offset:37632
	v_add_f32_dpp v24, v24, v24 row_ror:12 row_mask:0xf bank_mask:0x5
	v_add_f32_dpp v25, v25, v25 row_ror:4 row_mask:0xf bank_mask:0xa
	v_add_f32_dpp v22, v22, v22 quad_perm:[1,0,3,2] row_mask:0xf bank_mask:0xf
	v_add_f32_dpp v23, v23, v23 quad_perm:[1,0,3,2] row_mask:0xf bank_mask:0xf
	v_pk_mul_f32 v[84:85], v[2:3], v[40:41] op_sel:[0,0] op_sel_hi:[1,0]
	v_pk_mul_f32 v[86:87], v[4:5], v[40:41] op_sel:[0,1] op_sel_hi:[1,1]
	v_mov_b32_dpp v24, v25 quad_perm:[0,1,2,3] row_mask:0xf bank_mask:0xa
	v_add_f32_dpp v22, v22, v22 quad_perm:[2,3,0,1] row_mask:0xf bank_mask:0xf
	v_add_f32_dpp v23, v23, v23 quad_perm:[2,3,0,1] row_mask:0xf bank_mask:0xf
	v_pk_mul_f32 v[88:89], v[6:7], v[42:43] op_sel:[0,0] op_sel_hi:[1,0]
	v_pk_mul_f32 v[90:91], v[8:9], v[42:43] op_sel:[0,1] op_sel_hi:[1,1]
	v_add_f32_dpp v24, v24, v24 row_ror:8 row_mask:0xf bank_mask:0xf
	v_add_f32_dpp v22, v22, v22 row_half_mirror row_mask:0xf bank_mask:0xf
	v_add_f32_dpp v23, v23, v23 row_half_mirror row_mask:0xf bank_mask:0xf
	v_pk_fma_f32 v[84:85], v[48:49], v[56:57], v[84:85] op_sel:[0,0,0] op_sel_hi:[0,1,1]
	v_pk_fma_f32 v[86:87], v[48:49], v[56:57], v[86:87] op_sel:[1,0,0] op_sel_hi:[1,1,1]
	v_add_f32_dpp v24, v24, v24 quad_perm:[1,0,3,2] row_mask:0xf bank_mask:0xf
	v_add_f32_dpp v22, v22, v22 row_mirror row_mask:0xf bank_mask:0xf
	v_add_f32_dpp v23, v23, v23 row_mirror row_mask:0xf bank_mask:0xf
	v_pk_fma_f32 v[88:89], v[50:51], v[56:57], v[88:89] op_sel:[0,0,0] op_sel_hi:[0,1,1]
	v_pk_fma_f32 v[90:91], v[50:51], v[56:57], v[90:91] op_sel:[1,0,0] op_sel_hi:[1,1,1]
	v_add_f32_dpp v24, v24, v24 quad_perm:[2,3,0,1] row_mask:0xf bank_mask:0xf
	v_cndmask_b32_e64 v32, 0, v24, s[0:1]
	v_pk_fma_f32 v[2:3], v[44:45], v[22:23], v[84:85] op_sel:[0,0,0] op_sel_hi:[0,1,1] neg_lo:[1,0,0] neg_hi:[1,0,0]
	v_pk_fma_f32 v[4:5], v[44:45], v[22:23], v[86:87] op_sel:[1,0,0] op_sel_hi:[1,1,1] neg_lo:[1,0,0] neg_hi:[1,0,0]
	v_pk_fma_f32 v[6:7], v[46:47], v[22:23], v[88:89] op_sel:[0,0,0] op_sel_hi:[0,1,1] neg_lo:[1,0,0] neg_hi:[1,0,0]
	v_pk_fma_f32 v[8:9], v[46:47], v[22:23], v[90:91] op_sel:[1,0,0] op_sel_hi:[1,1,1] neg_lo:[1,0,0] neg_hi:[1,0,0]
	s_waitcnt lgkmcnt(0)
	v_pk_mul_f32 v[22:23], v[2:3], v[60:61] op_sel:[0,0] op_sel_hi:[1,0]
	v_pk_mul_f32 v[24:25], v[2:3], v[52:53] op_sel:[0,0] op_sel_hi:[1,0]
	ds_read_b128 v[36:39], v20 offset:5120
	v_pk_fma_f32 v[22:23], v[4:5], v[60:61], v[22:23] op_sel:[0,1,0] op_sel_hi:[1,1,1]
	v_pk_mul_f32 v[84:85], v[4:5], v[52:53] op_sel:[0,1] op_sel_hi:[1,1]
	ds_read_b128 v[40:43], v20 offset:13312
	v_pk_fma_f32 v[22:23], v[6:7], v[62:63], v[22:23] op_sel:[0,0,0] op_sel_hi:[1,0,1]
	v_pk_fma_f32 v[24:25], v[6:7], v[54:55], v[24:25] op_sel:[0,0,0] op_sel_hi:[1,0,1]
	ds_read_b64 v[56:57], v21 offset:46080
	v_pk_fma_f32 v[22:23], v[8:9], v[62:63], v[22:23] op_sel:[0,1,0] op_sel_hi:[1,1,1]
	v_pk_fma_f32 v[84:85], v[8:9], v[54:55], v[84:85] op_sel:[0,1,0] op_sel_hi:[1,1,1]
	ds_read_b128 v[48:51], v20 offset:29696
	v_pk_add_f32 v[24:25], v[24:25], v[84:85]
	ds_read_b128 v[44:47], v20 offset:21504
	ds_read_b128 v[52:55], v20 offset:37888
	v_add_f32_dpp v26, v26, v26 row_ror:12 row_mask:0xf bank_mask:0x5
	v_add_f32_dpp v27, v27, v27 row_ror:4 row_mask:0xf bank_mask:0xa
	v_add_f32_dpp v22, v22, v22 quad_perm:[1,0,3,2] row_mask:0xf bank_mask:0xf
	v_add_f32_dpp v23, v23, v23 quad_perm:[1,0,3,2] row_mask:0xf bank_mask:0xf
	v_pk_mul_f32 v[84:85], v[2:3], v[64:65] op_sel:[0,0] op_sel_hi:[1,0]
	v_pk_mul_f32 v[86:87], v[4:5], v[64:65] op_sel:[0,1] op_sel_hi:[1,1]
	v_mov_b32_dpp v26, v27 quad_perm:[0,1,2,3] row_mask:0xf bank_mask:0xa
	v_add_f32_dpp v22, v22, v22 quad_perm:[2,3,0,1] row_mask:0xf bank_mask:0xf
	v_add_f32_dpp v23, v23, v23 quad_perm:[2,3,0,1] row_mask:0xf bank_mask:0xf
	v_pk_mul_f32 v[88:89], v[6:7], v[66:67] op_sel:[0,0] op_sel_hi:[1,0]
	v_pk_mul_f32 v[90:91], v[8:9], v[66:67] op_sel:[0,1] op_sel_hi:[1,1]
	v_add_f32_dpp v26, v26, v26 row_ror:8 row_mask:0xf bank_mask:0xf
	v_add_f32_dpp v22, v22, v22 row_half_mirror row_mask:0xf bank_mask:0xf
	v_add_f32_dpp v23, v23, v23 row_half_mirror row_mask:0xf bank_mask:0xf
	v_pk_fma_f32 v[84:85], v[72:73], v[80:81], v[84:85] op_sel:[0,0,0] op_sel_hi:[0,1,1]
	v_pk_fma_f32 v[86:87], v[72:73], v[80:81], v[86:87] op_sel:[1,0,0] op_sel_hi:[1,1,1]
	v_add_f32_dpp v26, v26, v26 quad_perm:[1,0,3,2] row_mask:0xf bank_mask:0xf
	v_add_f32_dpp v22, v22, v22 row_mirror row_mask:0xf bank_mask:0xf
	v_add_f32_dpp v23, v23, v23 row_mirror row_mask:0xf bank_mask:0xf
	v_pk_fma_f32 v[88:89], v[74:75], v[80:81], v[88:89] op_sel:[0,0,0] op_sel_hi:[0,1,1]
	v_pk_fma_f32 v[90:91], v[74:75], v[80:81], v[90:91] op_sel:[1,0,0] op_sel_hi:[1,1,1]
	v_add_f32_dpp v26, v26, v26 quad_perm:[2,3,0,1] row_mask:0xf bank_mask:0xf
	v_cndmask_b32_e64 v32, v32, v26, s[6:7]
	v_pk_fma_f32 v[2:3], v[68:69], v[22:23], v[84:85] op_sel:[0,0,0] op_sel_hi:[0,1,1] neg_lo:[1,0,0] neg_hi:[1,0,0]
	v_pk_fma_f32 v[4:5], v[68:69], v[22:23], v[86:87] op_sel:[1,0,0] op_sel_hi:[1,1,1] neg_lo:[1,0,0] neg_hi:[1,0,0]
	v_pk_fma_f32 v[6:7], v[70:71], v[22:23], v[88:89] op_sel:[0,0,0] op_sel_hi:[0,1,1] neg_lo:[1,0,0] neg_hi:[1,0,0]
	v_pk_fma_f32 v[8:9], v[70:71], v[22:23], v[90:91] op_sel:[1,0,0] op_sel_hi:[1,1,1] neg_lo:[1,0,0] neg_hi:[1,0,0]
	s_waitcnt lgkmcnt(0)
	v_pk_mul_f32 v[22:23], v[2:3], v[36:37] op_sel:[0,0] op_sel_hi:[1,0]
	v_pk_mul_f32 v[26:27], v[2:3], v[76:77] op_sel:[0,0] op_sel_hi:[1,0]
	ds_read_b128 v[60:63], v20 offset:5376
	v_pk_fma_f32 v[22:23], v[4:5], v[36:37], v[22:23] op_sel:[0,1,0] op_sel_hi:[1,1,1]
	v_pk_mul_f32 v[84:85], v[4:5], v[76:77] op_sel:[0,1] op_sel_hi:[1,1]
	ds_read_b128 v[64:67], v20 offset:13568
	v_pk_fma_f32 v[22:23], v[6:7], v[38:39], v[22:23] op_sel:[0,0,0] op_sel_hi:[1,0,1]
	v_pk_fma_f32 v[26:27], v[6:7], v[78:79], v[26:27] op_sel:[0,0,0] op_sel_hi:[1,0,1]
	ds_read_b64 v[80:81], v21 offset:46336
	v_pk_fma_f32 v[22:23], v[8:9], v[38:39], v[22:23] op_sel:[0,1,0] op_sel_hi:[1,1,1]
	v_pk_fma_f32 v[84:85], v[8:9], v[78:79], v[84:85] op_sel:[0,1,0] op_sel_hi:[1,1,1]
	ds_read_b128 v[72:75], v20 offset:29952
	v_pk_add_f32 v[26:27], v[26:27], v[84:85]
	ds_read_b128 v[68:71], v20 offset:21760
	ds_read_b128 v[76:79], v20 offset:38144
	v_add_f32_dpp v24, v24, v24 row_ror:12 row_mask:0xf bank_mask:0x5
	v_add_f32_dpp v25, v25, v25 row_ror:4 row_mask:0xf bank_mask:0xa
	v_add_f32_dpp v22, v22, v22 quad_perm:[1,0,3,2] row_mask:0xf bank_mask:0xf
	v_add_f32_dpp v23, v23, v23 quad_perm:[1,0,3,2] row_mask:0xf bank_mask:0xf
	v_pk_mul_f32 v[84:85], v[2:3], v[40:41] op_sel:[0,0] op_sel_hi:[1,0]
	v_pk_mul_f32 v[86:87], v[4:5], v[40:41] op_sel:[0,1] op_sel_hi:[1,1]
	v_mov_b32_dpp v24, v25 quad_perm:[0,1,2,3] row_mask:0xf bank_mask:0xa
	v_add_f32_dpp v22, v22, v22 quad_perm:[2,3,0,1] row_mask:0xf bank_mask:0xf
	v_add_f32_dpp v23, v23, v23 quad_perm:[2,3,0,1] row_mask:0xf bank_mask:0xf
	v_pk_mul_f32 v[88:89], v[6:7], v[42:43] op_sel:[0,0] op_sel_hi:[1,0]
	v_pk_mul_f32 v[90:91], v[8:9], v[42:43] op_sel:[0,1] op_sel_hi:[1,1]
	v_add_f32_dpp v24, v24, v24 row_ror:8 row_mask:0xf bank_mask:0xf
	v_add_f32_dpp v22, v22, v22 row_half_mirror row_mask:0xf bank_mask:0xf
	v_add_f32_dpp v23, v23, v23 row_half_mirror row_mask:0xf bank_mask:0xf
	v_pk_fma_f32 v[84:85], v[48:49], v[56:57], v[84:85] op_sel:[0,0,0] op_sel_hi:[0,1,1]
	v_pk_fma_f32 v[86:87], v[48:49], v[56:57], v[86:87] op_sel:[1,0,0] op_sel_hi:[1,1,1]
	v_add_f32_dpp v24, v24, v24 quad_perm:[1,0,3,2] row_mask:0xf bank_mask:0xf
	v_add_f32_dpp v22, v22, v22 row_mirror row_mask:0xf bank_mask:0xf
	v_add_f32_dpp v23, v23, v23 row_mirror row_mask:0xf bank_mask:0xf
	v_pk_fma_f32 v[88:89], v[50:51], v[56:57], v[88:89] op_sel:[0,0,0] op_sel_hi:[0,1,1]
	v_pk_fma_f32 v[90:91], v[50:51], v[56:57], v[90:91] op_sel:[1,0,0] op_sel_hi:[1,1,1]
	v_add_f32_dpp v24, v24, v24 quad_perm:[2,3,0,1] row_mask:0xf bank_mask:0xf
	v_cndmask_b32_e64 v32, v32, v24, s[8:9]
	v_pk_fma_f32 v[2:3], v[44:45], v[22:23], v[84:85] op_sel:[0,0,0] op_sel_hi:[0,1,1] neg_lo:[1,0,0] neg_hi:[1,0,0]
	v_pk_fma_f32 v[4:5], v[44:45], v[22:23], v[86:87] op_sel:[1,0,0] op_sel_hi:[1,1,1] neg_lo:[1,0,0] neg_hi:[1,0,0]
	v_pk_fma_f32 v[6:7], v[46:47], v[22:23], v[88:89] op_sel:[0,0,0] op_sel_hi:[0,1,1] neg_lo:[1,0,0] neg_hi:[1,0,0]
	v_pk_fma_f32 v[8:9], v[46:47], v[22:23], v[90:91] op_sel:[1,0,0] op_sel_hi:[1,1,1] neg_lo:[1,0,0] neg_hi:[1,0,0]
	s_waitcnt lgkmcnt(0)
	v_pk_mul_f32 v[22:23], v[2:3], v[60:61] op_sel:[0,0] op_sel_hi:[1,0]
	v_pk_mul_f32 v[24:25], v[2:3], v[52:53] op_sel:[0,0] op_sel_hi:[1,0]
	ds_read_b128 v[36:39], v20 offset:5632
	v_pk_fma_f32 v[22:23], v[4:5], v[60:61], v[22:23] op_sel:[0,1,0] op_sel_hi:[1,1,1]
	v_pk_mul_f32 v[84:85], v[4:5], v[52:53] op_sel:[0,1] op_sel_hi:[1,1]
	ds_read_b128 v[40:43], v20 offset:13824
	v_pk_fma_f32 v[22:23], v[6:7], v[62:63], v[22:23] op_sel:[0,0,0] op_sel_hi:[1,0,1]
	v_pk_fma_f32 v[24:25], v[6:7], v[54:55], v[24:25] op_sel:[0,0,0] op_sel_hi:[1,0,1]
	ds_read_b64 v[56:57], v21 offset:46592
	v_pk_fma_f32 v[22:23], v[8:9], v[62:63], v[22:23] op_sel:[0,1,0] op_sel_hi:[1,1,1]
	v_pk_fma_f32 v[84:85], v[8:9], v[54:55], v[84:85] op_sel:[0,1,0] op_sel_hi:[1,1,1]
	ds_read_b128 v[48:51], v20 offset:30208
	v_pk_add_f32 v[24:25], v[24:25], v[84:85]
	ds_read_b128 v[44:47], v20 offset:22016
	ds_read_b128 v[52:55], v20 offset:38400
	v_add_f32_dpp v26, v26, v26 row_ror:12 row_mask:0xf bank_mask:0x5
	v_add_f32_dpp v27, v27, v27 row_ror:4 row_mask:0xf bank_mask:0xa
	v_add_f32_dpp v22, v22, v22 quad_perm:[1,0,3,2] row_mask:0xf bank_mask:0xf
	v_add_f32_dpp v23, v23, v23 quad_perm:[1,0,3,2] row_mask:0xf bank_mask:0xf
	v_pk_mul_f32 v[84:85], v[2:3], v[64:65] op_sel:[0,0] op_sel_hi:[1,0]
	v_pk_mul_f32 v[86:87], v[4:5], v[64:65] op_sel:[0,1] op_sel_hi:[1,1]
	v_mov_b32_dpp v26, v27 quad_perm:[0,1,2,3] row_mask:0xf bank_mask:0xa
	v_add_f32_dpp v22, v22, v22 quad_perm:[2,3,0,1] row_mask:0xf bank_mask:0xf
	v_add_f32_dpp v23, v23, v23 quad_perm:[2,3,0,1] row_mask:0xf bank_mask:0xf
	v_pk_mul_f32 v[88:89], v[6:7], v[66:67] op_sel:[0,0] op_sel_hi:[1,0]
	v_pk_mul_f32 v[90:91], v[8:9], v[66:67] op_sel:[0,1] op_sel_hi:[1,1]
	v_add_f32_dpp v26, v26, v26 row_ror:8 row_mask:0xf bank_mask:0xf
	v_add_f32_dpp v22, v22, v22 row_half_mirror row_mask:0xf bank_mask:0xf
	v_add_f32_dpp v23, v23, v23 row_half_mirror row_mask:0xf bank_mask:0xf
	v_pk_fma_f32 v[84:85], v[72:73], v[80:81], v[84:85] op_sel:[0,0,0] op_sel_hi:[0,1,1]
	v_pk_fma_f32 v[86:87], v[72:73], v[80:81], v[86:87] op_sel:[1,0,0] op_sel_hi:[1,1,1]
	v_add_f32_dpp v26, v26, v26 quad_perm:[1,0,3,2] row_mask:0xf bank_mask:0xf
	v_add_f32_dpp v22, v22, v22 row_mirror row_mask:0xf bank_mask:0xf
	v_add_f32_dpp v23, v23, v23 row_mirror row_mask:0xf bank_mask:0xf
	v_pk_fma_f32 v[88:89], v[74:75], v[80:81], v[88:89] op_sel:[0,0,0] op_sel_hi:[0,1,1]
	v_pk_fma_f32 v[90:91], v[74:75], v[80:81], v[90:91] op_sel:[1,0,0] op_sel_hi:[1,1,1]
	v_add_f32_dpp v26, v26, v26 quad_perm:[2,3,0,1] row_mask:0xf bank_mask:0xf
	v_cndmask_b32_e64 v32, v32, v26, s[10:11]
	v_pk_fma_f32 v[2:3], v[68:69], v[22:23], v[84:85] op_sel:[0,0,0] op_sel_hi:[0,1,1] neg_lo:[1,0,0] neg_hi:[1,0,0]
	v_pk_fma_f32 v[4:5], v[68:69], v[22:23], v[86:87] op_sel:[1,0,0] op_sel_hi:[1,1,1] neg_lo:[1,0,0] neg_hi:[1,0,0]
	v_pk_fma_f32 v[6:7], v[70:71], v[22:23], v[88:89] op_sel:[0,0,0] op_sel_hi:[0,1,1] neg_lo:[1,0,0] neg_hi:[1,0,0]
	v_pk_fma_f32 v[8:9], v[70:71], v[22:23], v[90:91] op_sel:[1,0,0] op_sel_hi:[1,1,1] neg_lo:[1,0,0] neg_hi:[1,0,0]
	s_waitcnt lgkmcnt(0)
	v_pk_mul_f32 v[22:23], v[2:3], v[36:37] op_sel:[0,0] op_sel_hi:[1,0]
	v_pk_mul_f32 v[26:27], v[2:3], v[76:77] op_sel:[0,0] op_sel_hi:[1,0]
	ds_read_b128 v[60:63], v20 offset:5888
	v_pk_fma_f32 v[22:23], v[4:5], v[36:37], v[22:23] op_sel:[0,1,0] op_sel_hi:[1,1,1]
	v_pk_mul_f32 v[84:85], v[4:5], v[76:77] op_sel:[0,1] op_sel_hi:[1,1]
	ds_read_b128 v[64:67], v20 offset:14080
	v_pk_fma_f32 v[22:23], v[6:7], v[38:39], v[22:23] op_sel:[0,0,0] op_sel_hi:[1,0,1]
	v_pk_fma_f32 v[26:27], v[6:7], v[78:79], v[26:27] op_sel:[0,0,0] op_sel_hi:[1,0,1]
	ds_read_b64 v[80:81], v21 offset:46848
	v_pk_fma_f32 v[22:23], v[8:9], v[38:39], v[22:23] op_sel:[0,1,0] op_sel_hi:[1,1,1]
	v_pk_fma_f32 v[84:85], v[8:9], v[78:79], v[84:85] op_sel:[0,1,0] op_sel_hi:[1,1,1]
	ds_read_b128 v[72:75], v20 offset:30464
	v_pk_add_f32 v[26:27], v[26:27], v[84:85]
	ds_read_b128 v[68:71], v20 offset:22272
	ds_read_b128 v[76:79], v20 offset:38656
	v_add_f32_dpp v24, v24, v24 row_ror:12 row_mask:0xf bank_mask:0x5
	v_add_f32_dpp v25, v25, v25 row_ror:4 row_mask:0xf bank_mask:0xa
	v_add_f32_dpp v22, v22, v22 quad_perm:[1,0,3,2] row_mask:0xf bank_mask:0xf
	v_add_f32_dpp v23, v23, v23 quad_perm:[1,0,3,2] row_mask:0xf bank_mask:0xf
	v_pk_mul_f32 v[84:85], v[2:3], v[40:41] op_sel:[0,0] op_sel_hi:[1,0]
	v_pk_mul_f32 v[86:87], v[4:5], v[40:41] op_sel:[0,1] op_sel_hi:[1,1]
	v_mov_b32_dpp v24, v25 quad_perm:[0,1,2,3] row_mask:0xf bank_mask:0xa
	v_add_f32_dpp v22, v22, v22 quad_perm:[2,3,0,1] row_mask:0xf bank_mask:0xf
	v_add_f32_dpp v23, v23, v23 quad_perm:[2,3,0,1] row_mask:0xf bank_mask:0xf
	v_pk_mul_f32 v[88:89], v[6:7], v[42:43] op_sel:[0,0] op_sel_hi:[1,0]
	v_pk_mul_f32 v[90:91], v[8:9], v[42:43] op_sel:[0,1] op_sel_hi:[1,1]
	v_add_f32_dpp v24, v24, v24 row_ror:8 row_mask:0xf bank_mask:0xf
	v_add_f32_dpp v22, v22, v22 row_half_mirror row_mask:0xf bank_mask:0xf
	v_add_f32_dpp v23, v23, v23 row_half_mirror row_mask:0xf bank_mask:0xf
	v_pk_fma_f32 v[84:85], v[48:49], v[56:57], v[84:85] op_sel:[0,0,0] op_sel_hi:[0,1,1]
	v_pk_fma_f32 v[86:87], v[48:49], v[56:57], v[86:87] op_sel:[1,0,0] op_sel_hi:[1,1,1]
	v_add_f32_dpp v24, v24, v24 quad_perm:[1,0,3,2] row_mask:0xf bank_mask:0xf
	v_add_f32_dpp v22, v22, v22 row_mirror row_mask:0xf bank_mask:0xf
	v_add_f32_dpp v23, v23, v23 row_mirror row_mask:0xf bank_mask:0xf
	v_pk_fma_f32 v[88:89], v[50:51], v[56:57], v[88:89] op_sel:[0,0,0] op_sel_hi:[0,1,1]
	v_pk_fma_f32 v[90:91], v[50:51], v[56:57], v[90:91] op_sel:[1,0,0] op_sel_hi:[1,1,1]
	v_add_f32_dpp v24, v24, v24 quad_perm:[2,3,0,1] row_mask:0xf bank_mask:0xf
	v_cndmask_b32_e64 v32, v32, v24, s[12:13]
	v_pk_fma_f32 v[2:3], v[44:45], v[22:23], v[84:85] op_sel:[0,0,0] op_sel_hi:[0,1,1] neg_lo:[1,0,0] neg_hi:[1,0,0]
	v_pk_fma_f32 v[4:5], v[44:45], v[22:23], v[86:87] op_sel:[1,0,0] op_sel_hi:[1,1,1] neg_lo:[1,0,0] neg_hi:[1,0,0]
	v_pk_fma_f32 v[6:7], v[46:47], v[22:23], v[88:89] op_sel:[0,0,0] op_sel_hi:[0,1,1] neg_lo:[1,0,0] neg_hi:[1,0,0]
	v_pk_fma_f32 v[8:9], v[46:47], v[22:23], v[90:91] op_sel:[1,0,0] op_sel_hi:[1,1,1] neg_lo:[1,0,0] neg_hi:[1,0,0]
	s_waitcnt lgkmcnt(0)
	v_pk_mul_f32 v[22:23], v[2:3], v[60:61] op_sel:[0,0] op_sel_hi:[1,0]
	v_pk_mul_f32 v[24:25], v[2:3], v[52:53] op_sel:[0,0] op_sel_hi:[1,0]
	ds_read_b128 v[36:39], v20 offset:6144
	v_pk_fma_f32 v[22:23], v[4:5], v[60:61], v[22:23] op_sel:[0,1,0] op_sel_hi:[1,1,1]
	v_pk_mul_f32 v[84:85], v[4:5], v[52:53] op_sel:[0,1] op_sel_hi:[1,1]
	ds_read_b128 v[40:43], v20 offset:14336
	v_pk_fma_f32 v[22:23], v[6:7], v[62:63], v[22:23] op_sel:[0,0,0] op_sel_hi:[1,0,1]
	v_pk_fma_f32 v[24:25], v[6:7], v[54:55], v[24:25] op_sel:[0,0,0] op_sel_hi:[1,0,1]
	ds_read_b64 v[56:57], v21 offset:47104
	v_pk_fma_f32 v[22:23], v[8:9], v[62:63], v[22:23] op_sel:[0,1,0] op_sel_hi:[1,1,1]
	v_pk_fma_f32 v[84:85], v[8:9], v[54:55], v[84:85] op_sel:[0,1,0] op_sel_hi:[1,1,1]
	ds_read_b128 v[48:51], v20 offset:30720
	v_pk_add_f32 v[24:25], v[24:25], v[84:85]
	ds_read_b128 v[44:47], v20 offset:22528
	ds_read_b128 v[52:55], v20 offset:38912
	v_add_f32_dpp v26, v26, v26 row_ror:12 row_mask:0xf bank_mask:0x5
	v_add_f32_dpp v27, v27, v27 row_ror:4 row_mask:0xf bank_mask:0xa
	v_add_f32_dpp v22, v22, v22 quad_perm:[1,0,3,2] row_mask:0xf bank_mask:0xf
	v_add_f32_dpp v23, v23, v23 quad_perm:[1,0,3,2] row_mask:0xf bank_mask:0xf
	v_pk_mul_f32 v[84:85], v[2:3], v[64:65] op_sel:[0,0] op_sel_hi:[1,0]
	v_pk_mul_f32 v[86:87], v[4:5], v[64:65] op_sel:[0,1] op_sel_hi:[1,1]
	v_mov_b32_dpp v26, v27 quad_perm:[0,1,2,3] row_mask:0xf bank_mask:0xa
	v_add_f32_dpp v22, v22, v22 quad_perm:[2,3,0,1] row_mask:0xf bank_mask:0xf
	v_add_f32_dpp v23, v23, v23 quad_perm:[2,3,0,1] row_mask:0xf bank_mask:0xf
	v_pk_mul_f32 v[88:89], v[6:7], v[66:67] op_sel:[0,0] op_sel_hi:[1,0]
	v_pk_mul_f32 v[90:91], v[8:9], v[66:67] op_sel:[0,1] op_sel_hi:[1,1]
	v_add_f32_dpp v26, v26, v26 row_ror:8 row_mask:0xf bank_mask:0xf
	v_add_f32_dpp v22, v22, v22 row_half_mirror row_mask:0xf bank_mask:0xf
	v_add_f32_dpp v23, v23, v23 row_half_mirror row_mask:0xf bank_mask:0xf
	v_pk_fma_f32 v[84:85], v[72:73], v[80:81], v[84:85] op_sel:[0,0,0] op_sel_hi:[0,1,1]
	v_pk_fma_f32 v[86:87], v[72:73], v[80:81], v[86:87] op_sel:[1,0,0] op_sel_hi:[1,1,1]
	v_add_f32_dpp v26, v26, v26 quad_perm:[1,0,3,2] row_mask:0xf bank_mask:0xf
	v_add_f32_dpp v22, v22, v22 row_mirror row_mask:0xf bank_mask:0xf
	v_add_f32_dpp v23, v23, v23 row_mirror row_mask:0xf bank_mask:0xf
	v_pk_fma_f32 v[88:89], v[74:75], v[80:81], v[88:89] op_sel:[0,0,0] op_sel_hi:[0,1,1]
	v_pk_fma_f32 v[90:91], v[74:75], v[80:81], v[90:91] op_sel:[1,0,0] op_sel_hi:[1,1,1]
	v_add_f32_dpp v26, v26, v26 quad_perm:[2,3,0,1] row_mask:0xf bank_mask:0xf
	v_cndmask_b32_e64 v32, v32, v26, s[14:15]
	v_pk_fma_f32 v[2:3], v[68:69], v[22:23], v[84:85] op_sel:[0,0,0] op_sel_hi:[0,1,1] neg_lo:[1,0,0] neg_hi:[1,0,0]
	v_pk_fma_f32 v[4:5], v[68:69], v[22:23], v[86:87] op_sel:[1,0,0] op_sel_hi:[1,1,1] neg_lo:[1,0,0] neg_hi:[1,0,0]
	v_pk_fma_f32 v[6:7], v[70:71], v[22:23], v[88:89] op_sel:[0,0,0] op_sel_hi:[0,1,1] neg_lo:[1,0,0] neg_hi:[1,0,0]
	v_pk_fma_f32 v[8:9], v[70:71], v[22:23], v[90:91] op_sel:[1,0,0] op_sel_hi:[1,1,1] neg_lo:[1,0,0] neg_hi:[1,0,0]
	s_waitcnt lgkmcnt(0)
	v_pk_mul_f32 v[22:23], v[2:3], v[36:37] op_sel:[0,0] op_sel_hi:[1,0]
	v_pk_mul_f32 v[26:27], v[2:3], v[76:77] op_sel:[0,0] op_sel_hi:[1,0]
	ds_read_b128 v[60:63], v20 offset:6400
	v_pk_fma_f32 v[22:23], v[4:5], v[36:37], v[22:23] op_sel:[0,1,0] op_sel_hi:[1,1,1]
	v_pk_mul_f32 v[84:85], v[4:5], v[76:77] op_sel:[0,1] op_sel_hi:[1,1]
	ds_read_b128 v[64:67], v20 offset:14592
	v_pk_fma_f32 v[22:23], v[6:7], v[38:39], v[22:23] op_sel:[0,0,0] op_sel_hi:[1,0,1]
	v_pk_fma_f32 v[26:27], v[6:7], v[78:79], v[26:27] op_sel:[0,0,0] op_sel_hi:[1,0,1]
	ds_read_b64 v[80:81], v21 offset:47360
	v_pk_fma_f32 v[22:23], v[8:9], v[38:39], v[22:23] op_sel:[0,1,0] op_sel_hi:[1,1,1]
	v_pk_fma_f32 v[84:85], v[8:9], v[78:79], v[84:85] op_sel:[0,1,0] op_sel_hi:[1,1,1]
	ds_read_b128 v[72:75], v20 offset:30976
	v_pk_add_f32 v[26:27], v[26:27], v[84:85]
	ds_read_b128 v[68:71], v20 offset:22784
	ds_read_b128 v[76:79], v20 offset:39168
	v_add_f32_dpp v24, v24, v24 row_ror:12 row_mask:0xf bank_mask:0x5
	v_add_f32_dpp v25, v25, v25 row_ror:4 row_mask:0xf bank_mask:0xa
	v_add_f32_dpp v22, v22, v22 quad_perm:[1,0,3,2] row_mask:0xf bank_mask:0xf
	v_add_f32_dpp v23, v23, v23 quad_perm:[1,0,3,2] row_mask:0xf bank_mask:0xf
	v_pk_mul_f32 v[84:85], v[2:3], v[40:41] op_sel:[0,0] op_sel_hi:[1,0]
	v_pk_mul_f32 v[86:87], v[4:5], v[40:41] op_sel:[0,1] op_sel_hi:[1,1]
	v_mov_b32_dpp v24, v25 quad_perm:[0,1,2,3] row_mask:0xf bank_mask:0xa
	v_add_f32_dpp v22, v22, v22 quad_perm:[2,3,0,1] row_mask:0xf bank_mask:0xf
	v_add_f32_dpp v23, v23, v23 quad_perm:[2,3,0,1] row_mask:0xf bank_mask:0xf
	v_pk_mul_f32 v[88:89], v[6:7], v[42:43] op_sel:[0,0] op_sel_hi:[1,0]
	v_pk_mul_f32 v[90:91], v[8:9], v[42:43] op_sel:[0,1] op_sel_hi:[1,1]
	v_add_f32_dpp v24, v24, v24 row_ror:8 row_mask:0xf bank_mask:0xf
	v_add_f32_dpp v22, v22, v22 row_half_mirror row_mask:0xf bank_mask:0xf
	v_add_f32_dpp v23, v23, v23 row_half_mirror row_mask:0xf bank_mask:0xf
	v_pk_fma_f32 v[84:85], v[48:49], v[56:57], v[84:85] op_sel:[0,0,0] op_sel_hi:[0,1,1]
	v_pk_fma_f32 v[86:87], v[48:49], v[56:57], v[86:87] op_sel:[1,0,0] op_sel_hi:[1,1,1]
	v_add_f32_dpp v24, v24, v24 quad_perm:[1,0,3,2] row_mask:0xf bank_mask:0xf
	v_add_f32_dpp v22, v22, v22 row_mirror row_mask:0xf bank_mask:0xf
	v_add_f32_dpp v23, v23, v23 row_mirror row_mask:0xf bank_mask:0xf
	v_pk_fma_f32 v[88:89], v[50:51], v[56:57], v[88:89] op_sel:[0,0,0] op_sel_hi:[0,1,1]
	v_pk_fma_f32 v[90:91], v[50:51], v[56:57], v[90:91] op_sel:[1,0,0] op_sel_hi:[1,1,1]
	v_add_f32_dpp v24, v24, v24 quad_perm:[2,3,0,1] row_mask:0xf bank_mask:0xf
	v_cndmask_b32_e64 v32, v32, v24, s[16:17]
	v_pk_fma_f32 v[2:3], v[44:45], v[22:23], v[84:85] op_sel:[0,0,0] op_sel_hi:[0,1,1] neg_lo:[1,0,0] neg_hi:[1,0,0]
	v_pk_fma_f32 v[4:5], v[44:45], v[22:23], v[86:87] op_sel:[1,0,0] op_sel_hi:[1,1,1] neg_lo:[1,0,0] neg_hi:[1,0,0]
	v_pk_fma_f32 v[6:7], v[46:47], v[22:23], v[88:89] op_sel:[0,0,0] op_sel_hi:[0,1,1] neg_lo:[1,0,0] neg_hi:[1,0,0]
	v_pk_fma_f32 v[8:9], v[46:47], v[22:23], v[90:91] op_sel:[1,0,0] op_sel_hi:[1,1,1] neg_lo:[1,0,0] neg_hi:[1,0,0]
	s_waitcnt lgkmcnt(0)
	v_pk_mul_f32 v[22:23], v[2:3], v[60:61] op_sel:[0,0] op_sel_hi:[1,0]
	v_pk_mul_f32 v[24:25], v[2:3], v[52:53] op_sel:[0,0] op_sel_hi:[1,0]
	ds_read_b128 v[36:39], v20 offset:6656
	v_pk_fma_f32 v[22:23], v[4:5], v[60:61], v[22:23] op_sel:[0,1,0] op_sel_hi:[1,1,1]
	v_pk_mul_f32 v[84:85], v[4:5], v[52:53] op_sel:[0,1] op_sel_hi:[1,1]
	ds_read_b128 v[40:43], v20 offset:14848
	v_pk_fma_f32 v[22:23], v[6:7], v[62:63], v[22:23] op_sel:[0,0,0] op_sel_hi:[1,0,1]
	v_pk_fma_f32 v[24:25], v[6:7], v[54:55], v[24:25] op_sel:[0,0,0] op_sel_hi:[1,0,1]
	ds_read_b64 v[56:57], v21 offset:47616
	v_pk_fma_f32 v[22:23], v[8:9], v[62:63], v[22:23] op_sel:[0,1,0] op_sel_hi:[1,1,1]
	v_pk_fma_f32 v[84:85], v[8:9], v[54:55], v[84:85] op_sel:[0,1,0] op_sel_hi:[1,1,1]
	ds_read_b128 v[48:51], v20 offset:31232
	v_pk_add_f32 v[24:25], v[24:25], v[84:85]
	ds_read_b128 v[44:47], v20 offset:23040
	ds_read_b128 v[52:55], v20 offset:39424
	v_add_f32_dpp v26, v26, v26 row_ror:12 row_mask:0xf bank_mask:0x5
	v_add_f32_dpp v27, v27, v27 row_ror:4 row_mask:0xf bank_mask:0xa
	v_add_f32_dpp v22, v22, v22 quad_perm:[1,0,3,2] row_mask:0xf bank_mask:0xf
	v_add_f32_dpp v23, v23, v23 quad_perm:[1,0,3,2] row_mask:0xf bank_mask:0xf
	v_pk_mul_f32 v[84:85], v[2:3], v[64:65] op_sel:[0,0] op_sel_hi:[1,0]
	v_pk_mul_f32 v[86:87], v[4:5], v[64:65] op_sel:[0,1] op_sel_hi:[1,1]
	v_mov_b32_dpp v26, v27 quad_perm:[0,1,2,3] row_mask:0xf bank_mask:0xa
	v_add_f32_dpp v22, v22, v22 quad_perm:[2,3,0,1] row_mask:0xf bank_mask:0xf
	v_add_f32_dpp v23, v23, v23 quad_perm:[2,3,0,1] row_mask:0xf bank_mask:0xf
	v_pk_mul_f32 v[88:89], v[6:7], v[66:67] op_sel:[0,0] op_sel_hi:[1,0]
	v_pk_mul_f32 v[90:91], v[8:9], v[66:67] op_sel:[0,1] op_sel_hi:[1,1]
	v_add_f32_dpp v26, v26, v26 row_ror:8 row_mask:0xf bank_mask:0xf
	v_add_f32_dpp v22, v22, v22 row_half_mirror row_mask:0xf bank_mask:0xf
	v_add_f32_dpp v23, v23, v23 row_half_mirror row_mask:0xf bank_mask:0xf
	v_pk_fma_f32 v[84:85], v[72:73], v[80:81], v[84:85] op_sel:[0,0,0] op_sel_hi:[0,1,1]
	v_pk_fma_f32 v[86:87], v[72:73], v[80:81], v[86:87] op_sel:[1,0,0] op_sel_hi:[1,1,1]
	v_add_f32_dpp v26, v26, v26 quad_perm:[1,0,3,2] row_mask:0xf bank_mask:0xf
	v_add_f32_dpp v22, v22, v22 row_mirror row_mask:0xf bank_mask:0xf
	v_add_f32_dpp v23, v23, v23 row_mirror row_mask:0xf bank_mask:0xf
	v_pk_fma_f32 v[88:89], v[74:75], v[80:81], v[88:89] op_sel:[0,0,0] op_sel_hi:[0,1,1]
	v_pk_fma_f32 v[90:91], v[74:75], v[80:81], v[90:91] op_sel:[1,0,0] op_sel_hi:[1,1,1]
	v_add_f32_dpp v26, v26, v26 quad_perm:[2,3,0,1] row_mask:0xf bank_mask:0xf
	v_cndmask_b32_e32 v32, v32, v26, vcc
	v_pk_fma_f32 v[2:3], v[68:69], v[22:23], v[84:85] op_sel:[0,0,0] op_sel_hi:[0,1,1] neg_lo:[1,0,0] neg_hi:[1,0,0]
	v_pk_fma_f32 v[4:5], v[68:69], v[22:23], v[86:87] op_sel:[1,0,0] op_sel_hi:[1,1,1] neg_lo:[1,0,0] neg_hi:[1,0,0]
	v_pk_fma_f32 v[6:7], v[70:71], v[22:23], v[88:89] op_sel:[0,0,0] op_sel_hi:[0,1,1] neg_lo:[1,0,0] neg_hi:[1,0,0]
	v_pk_fma_f32 v[8:9], v[70:71], v[22:23], v[90:91] op_sel:[1,0,0] op_sel_hi:[1,1,1] neg_lo:[1,0,0] neg_hi:[1,0,0]
	s_waitcnt lgkmcnt(0)
	v_pk_mul_f32 v[22:23], v[2:3], v[36:37] op_sel:[0,0] op_sel_hi:[1,0]
	v_pk_mul_f32 v[26:27], v[2:3], v[76:77] op_sel:[0,0] op_sel_hi:[1,0]
	ds_read_b128 v[60:63], v20 offset:6912
	v_pk_fma_f32 v[22:23], v[4:5], v[36:37], v[22:23] op_sel:[0,1,0] op_sel_hi:[1,1,1]
	v_pk_mul_f32 v[84:85], v[4:5], v[76:77] op_sel:[0,1] op_sel_hi:[1,1]
	ds_read_b128 v[64:67], v20 offset:15104
	v_pk_fma_f32 v[22:23], v[6:7], v[38:39], v[22:23] op_sel:[0,0,0] op_sel_hi:[1,0,1]
	v_pk_fma_f32 v[26:27], v[6:7], v[78:79], v[26:27] op_sel:[0,0,0] op_sel_hi:[1,0,1]
	ds_read_b64 v[80:81], v21 offset:47872
	v_pk_fma_f32 v[22:23], v[8:9], v[38:39], v[22:23] op_sel:[0,1,0] op_sel_hi:[1,1,1]
	v_pk_fma_f32 v[84:85], v[8:9], v[78:79], v[84:85] op_sel:[0,1,0] op_sel_hi:[1,1,1]
	ds_read_b128 v[72:75], v20 offset:31488
	v_pk_add_f32 v[26:27], v[26:27], v[84:85]
	ds_read_b128 v[68:71], v20 offset:23296
	ds_read_b128 v[76:79], v20 offset:39680
	v_add_f32_dpp v24, v24, v24 row_ror:12 row_mask:0xf bank_mask:0x5
	v_add_f32_dpp v25, v25, v25 row_ror:4 row_mask:0xf bank_mask:0xa
	v_add_f32_dpp v22, v22, v22 quad_perm:[1,0,3,2] row_mask:0xf bank_mask:0xf
	v_add_f32_dpp v23, v23, v23 quad_perm:[1,0,3,2] row_mask:0xf bank_mask:0xf
	v_pk_mul_f32 v[84:85], v[2:3], v[40:41] op_sel:[0,0] op_sel_hi:[1,0]
	v_pk_mul_f32 v[86:87], v[4:5], v[40:41] op_sel:[0,1] op_sel_hi:[1,1]
	v_mov_b32_dpp v24, v25 quad_perm:[0,1,2,3] row_mask:0xf bank_mask:0xa
	v_add_f32_dpp v22, v22, v22 quad_perm:[2,3,0,1] row_mask:0xf bank_mask:0xf
	v_add_f32_dpp v23, v23, v23 quad_perm:[2,3,0,1] row_mask:0xf bank_mask:0xf
	v_pk_mul_f32 v[88:89], v[6:7], v[42:43] op_sel:[0,0] op_sel_hi:[1,0]
	v_pk_mul_f32 v[90:91], v[8:9], v[42:43] op_sel:[0,1] op_sel_hi:[1,1]
	v_add_f32_dpp v24, v24, v24 row_ror:8 row_mask:0xf bank_mask:0xf
	v_add_f32_dpp v22, v22, v22 row_half_mirror row_mask:0xf bank_mask:0xf
	v_add_f32_dpp v23, v23, v23 row_half_mirror row_mask:0xf bank_mask:0xf
	v_pk_fma_f32 v[84:85], v[48:49], v[56:57], v[84:85] op_sel:[0,0,0] op_sel_hi:[0,1,1]
	v_pk_fma_f32 v[86:87], v[48:49], v[56:57], v[86:87] op_sel:[1,0,0] op_sel_hi:[1,1,1]
	v_add_f32_dpp v24, v24, v24 quad_perm:[1,0,3,2] row_mask:0xf bank_mask:0xf
	v_add_f32_dpp v22, v22, v22 row_mirror row_mask:0xf bank_mask:0xf
	v_add_f32_dpp v23, v23, v23 row_mirror row_mask:0xf bank_mask:0xf
	v_pk_fma_f32 v[88:89], v[50:51], v[56:57], v[88:89] op_sel:[0,0,0] op_sel_hi:[0,1,1]
	v_pk_fma_f32 v[90:91], v[50:51], v[56:57], v[90:91] op_sel:[1,0,0] op_sel_hi:[1,1,1]
	v_add_f32_dpp v24, v24, v24 quad_perm:[2,3,0,1] row_mask:0xf bank_mask:0xf
	v_cndmask_b32_e64 v33, 0, v24, s[0:1]
	v_pk_fma_f32 v[2:3], v[44:45], v[22:23], v[84:85] op_sel:[0,0,0] op_sel_hi:[0,1,1] neg_lo:[1,0,0] neg_hi:[1,0,0]
	v_pk_fma_f32 v[4:5], v[44:45], v[22:23], v[86:87] op_sel:[1,0,0] op_sel_hi:[1,1,1] neg_lo:[1,0,0] neg_hi:[1,0,0]
	v_pk_fma_f32 v[6:7], v[46:47], v[22:23], v[88:89] op_sel:[0,0,0] op_sel_hi:[0,1,1] neg_lo:[1,0,0] neg_hi:[1,0,0]
	v_pk_fma_f32 v[8:9], v[46:47], v[22:23], v[90:91] op_sel:[1,0,0] op_sel_hi:[1,1,1] neg_lo:[1,0,0] neg_hi:[1,0,0]
	s_waitcnt lgkmcnt(0)
	v_pk_mul_f32 v[22:23], v[2:3], v[60:61] op_sel:[0,0] op_sel_hi:[1,0]
	v_pk_mul_f32 v[24:25], v[2:3], v[52:53] op_sel:[0,0] op_sel_hi:[1,0]
	ds_read_b128 v[36:39], v20 offset:7168
	v_pk_fma_f32 v[22:23], v[4:5], v[60:61], v[22:23] op_sel:[0,1,0] op_sel_hi:[1,1,1]
	v_pk_mul_f32 v[84:85], v[4:5], v[52:53] op_sel:[0,1] op_sel_hi:[1,1]
	ds_read_b128 v[40:43], v20 offset:15360
	v_pk_fma_f32 v[22:23], v[6:7], v[62:63], v[22:23] op_sel:[0,0,0] op_sel_hi:[1,0,1]
	v_pk_fma_f32 v[24:25], v[6:7], v[54:55], v[24:25] op_sel:[0,0,0] op_sel_hi:[1,0,1]
	ds_read_b64 v[56:57], v21 offset:48128
	v_pk_fma_f32 v[22:23], v[8:9], v[62:63], v[22:23] op_sel:[0,1,0] op_sel_hi:[1,1,1]
	v_pk_fma_f32 v[84:85], v[8:9], v[54:55], v[84:85] op_sel:[0,1,0] op_sel_hi:[1,1,1]
	ds_read_b128 v[48:51], v20 offset:31744
	v_pk_add_f32 v[24:25], v[24:25], v[84:85]
	ds_read_b128 v[44:47], v20 offset:23552
	ds_read_b128 v[52:55], v20 offset:39936
	v_add_f32_dpp v26, v26, v26 row_ror:12 row_mask:0xf bank_mask:0x5
	v_add_f32_dpp v27, v27, v27 row_ror:4 row_mask:0xf bank_mask:0xa
	v_add_f32_dpp v22, v22, v22 quad_perm:[1,0,3,2] row_mask:0xf bank_mask:0xf
	v_add_f32_dpp v23, v23, v23 quad_perm:[1,0,3,2] row_mask:0xf bank_mask:0xf
	v_pk_mul_f32 v[84:85], v[2:3], v[64:65] op_sel:[0,0] op_sel_hi:[1,0]
	v_pk_mul_f32 v[86:87], v[4:5], v[64:65] op_sel:[0,1] op_sel_hi:[1,1]
	v_mov_b32_dpp v26, v27 quad_perm:[0,1,2,3] row_mask:0xf bank_mask:0xa
	v_add_f32_dpp v22, v22, v22 quad_perm:[2,3,0,1] row_mask:0xf bank_mask:0xf
	v_add_f32_dpp v23, v23, v23 quad_perm:[2,3,0,1] row_mask:0xf bank_mask:0xf
	v_pk_mul_f32 v[88:89], v[6:7], v[66:67] op_sel:[0,0] op_sel_hi:[1,0]
	v_pk_mul_f32 v[90:91], v[8:9], v[66:67] op_sel:[0,1] op_sel_hi:[1,1]
	v_add_f32_dpp v26, v26, v26 row_ror:8 row_mask:0xf bank_mask:0xf
	v_add_f32_dpp v22, v22, v22 row_half_mirror row_mask:0xf bank_mask:0xf
	v_add_f32_dpp v23, v23, v23 row_half_mirror row_mask:0xf bank_mask:0xf
	v_pk_fma_f32 v[84:85], v[72:73], v[80:81], v[84:85] op_sel:[0,0,0] op_sel_hi:[0,1,1]
	v_pk_fma_f32 v[86:87], v[72:73], v[80:81], v[86:87] op_sel:[1,0,0] op_sel_hi:[1,1,1]
	v_add_f32_dpp v26, v26, v26 quad_perm:[1,0,3,2] row_mask:0xf bank_mask:0xf
	v_add_f32_dpp v22, v22, v22 row_mirror row_mask:0xf bank_mask:0xf
	v_add_f32_dpp v23, v23, v23 row_mirror row_mask:0xf bank_mask:0xf
	v_pk_fma_f32 v[88:89], v[74:75], v[80:81], v[88:89] op_sel:[0,0,0] op_sel_hi:[0,1,1]
	v_pk_fma_f32 v[90:91], v[74:75], v[80:81], v[90:91] op_sel:[1,0,0] op_sel_hi:[1,1,1]
	v_add_f32_dpp v26, v26, v26 quad_perm:[2,3,0,1] row_mask:0xf bank_mask:0xf
	v_cndmask_b32_e64 v33, v33, v26, s[6:7]
	v_pk_fma_f32 v[2:3], v[68:69], v[22:23], v[84:85] op_sel:[0,0,0] op_sel_hi:[0,1,1] neg_lo:[1,0,0] neg_hi:[1,0,0]
	v_pk_fma_f32 v[4:5], v[68:69], v[22:23], v[86:87] op_sel:[1,0,0] op_sel_hi:[1,1,1] neg_lo:[1,0,0] neg_hi:[1,0,0]
	v_pk_fma_f32 v[6:7], v[70:71], v[22:23], v[88:89] op_sel:[0,0,0] op_sel_hi:[0,1,1] neg_lo:[1,0,0] neg_hi:[1,0,0]
	v_pk_fma_f32 v[8:9], v[70:71], v[22:23], v[90:91] op_sel:[1,0,0] op_sel_hi:[1,1,1] neg_lo:[1,0,0] neg_hi:[1,0,0]
	s_waitcnt lgkmcnt(0)
	v_pk_mul_f32 v[22:23], v[2:3], v[36:37] op_sel:[0,0] op_sel_hi:[1,0]
	v_pk_mul_f32 v[26:27], v[2:3], v[76:77] op_sel:[0,0] op_sel_hi:[1,0]
	ds_read_b128 v[60:63], v20 offset:7424
	v_pk_fma_f32 v[22:23], v[4:5], v[36:37], v[22:23] op_sel:[0,1,0] op_sel_hi:[1,1,1]
	v_pk_mul_f32 v[84:85], v[4:5], v[76:77] op_sel:[0,1] op_sel_hi:[1,1]
	ds_read_b128 v[64:67], v20 offset:15616
	v_pk_fma_f32 v[22:23], v[6:7], v[38:39], v[22:23] op_sel:[0,0,0] op_sel_hi:[1,0,1]
	v_pk_fma_f32 v[26:27], v[6:7], v[78:79], v[26:27] op_sel:[0,0,0] op_sel_hi:[1,0,1]
	ds_read_b64 v[80:81], v21 offset:48384
	v_pk_fma_f32 v[22:23], v[8:9], v[38:39], v[22:23] op_sel:[0,1,0] op_sel_hi:[1,1,1]
	v_pk_fma_f32 v[84:85], v[8:9], v[78:79], v[84:85] op_sel:[0,1,0] op_sel_hi:[1,1,1]
	ds_read_b128 v[72:75], v20 offset:32000
	v_pk_add_f32 v[26:27], v[26:27], v[84:85]
	ds_read_b128 v[68:71], v20 offset:23808
	ds_read_b128 v[76:79], v20 offset:40192
	v_add_f32_dpp v24, v24, v24 row_ror:12 row_mask:0xf bank_mask:0x5
	v_add_f32_dpp v25, v25, v25 row_ror:4 row_mask:0xf bank_mask:0xa
	v_add_f32_dpp v22, v22, v22 quad_perm:[1,0,3,2] row_mask:0xf bank_mask:0xf
	v_add_f32_dpp v23, v23, v23 quad_perm:[1,0,3,2] row_mask:0xf bank_mask:0xf
	v_pk_mul_f32 v[84:85], v[2:3], v[40:41] op_sel:[0,0] op_sel_hi:[1,0]
	v_pk_mul_f32 v[86:87], v[4:5], v[40:41] op_sel:[0,1] op_sel_hi:[1,1]
	v_mov_b32_dpp v24, v25 quad_perm:[0,1,2,3] row_mask:0xf bank_mask:0xa
	v_add_f32_dpp v22, v22, v22 quad_perm:[2,3,0,1] row_mask:0xf bank_mask:0xf
	v_add_f32_dpp v23, v23, v23 quad_perm:[2,3,0,1] row_mask:0xf bank_mask:0xf
	v_pk_mul_f32 v[88:89], v[6:7], v[42:43] op_sel:[0,0] op_sel_hi:[1,0]
	v_pk_mul_f32 v[90:91], v[8:9], v[42:43] op_sel:[0,1] op_sel_hi:[1,1]
	v_add_f32_dpp v24, v24, v24 row_ror:8 row_mask:0xf bank_mask:0xf
	v_add_f32_dpp v22, v22, v22 row_half_mirror row_mask:0xf bank_mask:0xf
	v_add_f32_dpp v23, v23, v23 row_half_mirror row_mask:0xf bank_mask:0xf
	v_pk_fma_f32 v[84:85], v[48:49], v[56:57], v[84:85] op_sel:[0,0,0] op_sel_hi:[0,1,1]
	v_pk_fma_f32 v[86:87], v[48:49], v[56:57], v[86:87] op_sel:[1,0,0] op_sel_hi:[1,1,1]
	v_add_f32_dpp v24, v24, v24 quad_perm:[1,0,3,2] row_mask:0xf bank_mask:0xf
	v_add_f32_dpp v22, v22, v22 row_mirror row_mask:0xf bank_mask:0xf
	v_add_f32_dpp v23, v23, v23 row_mirror row_mask:0xf bank_mask:0xf
	v_pk_fma_f32 v[88:89], v[50:51], v[56:57], v[88:89] op_sel:[0,0,0] op_sel_hi:[0,1,1]
	v_pk_fma_f32 v[90:91], v[50:51], v[56:57], v[90:91] op_sel:[1,0,0] op_sel_hi:[1,1,1]
	v_add_f32_dpp v24, v24, v24 quad_perm:[2,3,0,1] row_mask:0xf bank_mask:0xf
	v_cndmask_b32_e64 v33, v33, v24, s[8:9]
	v_pk_fma_f32 v[2:3], v[44:45], v[22:23], v[84:85] op_sel:[0,0,0] op_sel_hi:[0,1,1] neg_lo:[1,0,0] neg_hi:[1,0,0]
	v_pk_fma_f32 v[4:5], v[44:45], v[22:23], v[86:87] op_sel:[1,0,0] op_sel_hi:[1,1,1] neg_lo:[1,0,0] neg_hi:[1,0,0]
	v_pk_fma_f32 v[6:7], v[46:47], v[22:23], v[88:89] op_sel:[0,0,0] op_sel_hi:[0,1,1] neg_lo:[1,0,0] neg_hi:[1,0,0]
	v_pk_fma_f32 v[8:9], v[46:47], v[22:23], v[90:91] op_sel:[1,0,0] op_sel_hi:[1,1,1] neg_lo:[1,0,0] neg_hi:[1,0,0]
	s_waitcnt lgkmcnt(0)
	v_pk_mul_f32 v[22:23], v[2:3], v[60:61] op_sel:[0,0] op_sel_hi:[1,0]
	v_pk_mul_f32 v[24:25], v[2:3], v[52:53] op_sel:[0,0] op_sel_hi:[1,0]
	ds_read_b128 v[36:39], v20 offset:7680
	v_pk_fma_f32 v[22:23], v[4:5], v[60:61], v[22:23] op_sel:[0,1,0] op_sel_hi:[1,1,1]
	v_pk_mul_f32 v[84:85], v[4:5], v[52:53] op_sel:[0,1] op_sel_hi:[1,1]
	ds_read_b128 v[40:43], v20 offset:15872
	v_pk_fma_f32 v[22:23], v[6:7], v[62:63], v[22:23] op_sel:[0,0,0] op_sel_hi:[1,0,1]
	v_pk_fma_f32 v[24:25], v[6:7], v[54:55], v[24:25] op_sel:[0,0,0] op_sel_hi:[1,0,1]
	ds_read_b64 v[56:57], v21 offset:48640
	v_pk_fma_f32 v[22:23], v[8:9], v[62:63], v[22:23] op_sel:[0,1,0] op_sel_hi:[1,1,1]
	v_pk_fma_f32 v[84:85], v[8:9], v[54:55], v[84:85] op_sel:[0,1,0] op_sel_hi:[1,1,1]
	ds_read_b128 v[48:51], v20 offset:32256
	v_pk_add_f32 v[24:25], v[24:25], v[84:85]
	ds_read_b128 v[44:47], v20 offset:24064
	ds_read_b128 v[52:55], v20 offset:40448
	v_add_f32_dpp v26, v26, v26 row_ror:12 row_mask:0xf bank_mask:0x5
	v_add_f32_dpp v27, v27, v27 row_ror:4 row_mask:0xf bank_mask:0xa
	v_add_f32_dpp v22, v22, v22 quad_perm:[1,0,3,2] row_mask:0xf bank_mask:0xf
	v_add_f32_dpp v23, v23, v23 quad_perm:[1,0,3,2] row_mask:0xf bank_mask:0xf
	v_pk_mul_f32 v[84:85], v[2:3], v[64:65] op_sel:[0,0] op_sel_hi:[1,0]
	v_pk_mul_f32 v[86:87], v[4:5], v[64:65] op_sel:[0,1] op_sel_hi:[1,1]
	v_mov_b32_dpp v26, v27 quad_perm:[0,1,2,3] row_mask:0xf bank_mask:0xa
	v_add_f32_dpp v22, v22, v22 quad_perm:[2,3,0,1] row_mask:0xf bank_mask:0xf
	v_add_f32_dpp v23, v23, v23 quad_perm:[2,3,0,1] row_mask:0xf bank_mask:0xf
	v_pk_mul_f32 v[88:89], v[6:7], v[66:67] op_sel:[0,0] op_sel_hi:[1,0]
	v_pk_mul_f32 v[90:91], v[8:9], v[66:67] op_sel:[0,1] op_sel_hi:[1,1]
	v_add_f32_dpp v26, v26, v26 row_ror:8 row_mask:0xf bank_mask:0xf
	v_add_f32_dpp v22, v22, v22 row_half_mirror row_mask:0xf bank_mask:0xf
	v_add_f32_dpp v23, v23, v23 row_half_mirror row_mask:0xf bank_mask:0xf
	v_pk_fma_f32 v[84:85], v[72:73], v[80:81], v[84:85] op_sel:[0,0,0] op_sel_hi:[0,1,1]
	v_pk_fma_f32 v[86:87], v[72:73], v[80:81], v[86:87] op_sel:[1,0,0] op_sel_hi:[1,1,1]
	v_add_f32_dpp v26, v26, v26 quad_perm:[1,0,3,2] row_mask:0xf bank_mask:0xf
	v_add_f32_dpp v22, v22, v22 row_mirror row_mask:0xf bank_mask:0xf
	v_add_f32_dpp v23, v23, v23 row_mirror row_mask:0xf bank_mask:0xf
	v_pk_fma_f32 v[88:89], v[74:75], v[80:81], v[88:89] op_sel:[0,0,0] op_sel_hi:[0,1,1]
	v_pk_fma_f32 v[90:91], v[74:75], v[80:81], v[90:91] op_sel:[1,0,0] op_sel_hi:[1,1,1]
	v_add_f32_dpp v26, v26, v26 quad_perm:[2,3,0,1] row_mask:0xf bank_mask:0xf
	v_cndmask_b32_e64 v33, v33, v26, s[10:11]
	v_pk_fma_f32 v[2:3], v[68:69], v[22:23], v[84:85] op_sel:[0,0,0] op_sel_hi:[0,1,1] neg_lo:[1,0,0] neg_hi:[1,0,0]
	v_pk_fma_f32 v[4:5], v[68:69], v[22:23], v[86:87] op_sel:[1,0,0] op_sel_hi:[1,1,1] neg_lo:[1,0,0] neg_hi:[1,0,0]
	v_pk_fma_f32 v[6:7], v[70:71], v[22:23], v[88:89] op_sel:[0,0,0] op_sel_hi:[0,1,1] neg_lo:[1,0,0] neg_hi:[1,0,0]
	v_pk_fma_f32 v[8:9], v[70:71], v[22:23], v[90:91] op_sel:[1,0,0] op_sel_hi:[1,1,1] neg_lo:[1,0,0] neg_hi:[1,0,0]
	s_waitcnt lgkmcnt(0)
	v_pk_mul_f32 v[22:23], v[2:3], v[36:37] op_sel:[0,0] op_sel_hi:[1,0]
	v_pk_mul_f32 v[26:27], v[2:3], v[76:77] op_sel:[0,0] op_sel_hi:[1,0]
	ds_read_b128 v[60:63], v20 offset:7936
	v_pk_fma_f32 v[22:23], v[4:5], v[36:37], v[22:23] op_sel:[0,1,0] op_sel_hi:[1,1,1]
	v_pk_mul_f32 v[84:85], v[4:5], v[76:77] op_sel:[0,1] op_sel_hi:[1,1]
	ds_read_b128 v[64:67], v20 offset:16128
	v_pk_fma_f32 v[22:23], v[6:7], v[38:39], v[22:23] op_sel:[0,0,0] op_sel_hi:[1,0,1]
	v_pk_fma_f32 v[26:27], v[6:7], v[78:79], v[26:27] op_sel:[0,0,0] op_sel_hi:[1,0,1]
	ds_read_b64 v[80:81], v21 offset:48896
	v_pk_fma_f32 v[22:23], v[8:9], v[38:39], v[22:23] op_sel:[0,1,0] op_sel_hi:[1,1,1]
	v_pk_fma_f32 v[84:85], v[8:9], v[78:79], v[84:85] op_sel:[0,1,0] op_sel_hi:[1,1,1]
	ds_read_b128 v[72:75], v20 offset:32512
	v_pk_add_f32 v[26:27], v[26:27], v[84:85]
	ds_read_b128 v[68:71], v20 offset:24320
	ds_read_b128 v[76:79], v20 offset:40704
	v_add_f32_dpp v24, v24, v24 row_ror:12 row_mask:0xf bank_mask:0x5
	v_add_f32_dpp v25, v25, v25 row_ror:4 row_mask:0xf bank_mask:0xa
	v_add_f32_dpp v22, v22, v22 quad_perm:[1,0,3,2] row_mask:0xf bank_mask:0xf
	v_add_f32_dpp v23, v23, v23 quad_perm:[1,0,3,2] row_mask:0xf bank_mask:0xf
	v_pk_mul_f32 v[84:85], v[2:3], v[40:41] op_sel:[0,0] op_sel_hi:[1,0]
	v_pk_mul_f32 v[86:87], v[4:5], v[40:41] op_sel:[0,1] op_sel_hi:[1,1]
	v_mov_b32_dpp v24, v25 quad_perm:[0,1,2,3] row_mask:0xf bank_mask:0xa
	v_add_f32_dpp v22, v22, v22 quad_perm:[2,3,0,1] row_mask:0xf bank_mask:0xf
	v_add_f32_dpp v23, v23, v23 quad_perm:[2,3,0,1] row_mask:0xf bank_mask:0xf
	v_pk_mul_f32 v[88:89], v[6:7], v[42:43] op_sel:[0,0] op_sel_hi:[1,0]
	v_pk_mul_f32 v[90:91], v[8:9], v[42:43] op_sel:[0,1] op_sel_hi:[1,1]
	v_add_f32_dpp v24, v24, v24 row_ror:8 row_mask:0xf bank_mask:0xf
	v_add_f32_dpp v22, v22, v22 row_half_mirror row_mask:0xf bank_mask:0xf
	v_add_f32_dpp v23, v23, v23 row_half_mirror row_mask:0xf bank_mask:0xf
	v_pk_fma_f32 v[84:85], v[48:49], v[56:57], v[84:85] op_sel:[0,0,0] op_sel_hi:[0,1,1]
	v_pk_fma_f32 v[86:87], v[48:49], v[56:57], v[86:87] op_sel:[1,0,0] op_sel_hi:[1,1,1]
	v_add_f32_dpp v24, v24, v24 quad_perm:[1,0,3,2] row_mask:0xf bank_mask:0xf
	v_add_f32_dpp v22, v22, v22 row_mirror row_mask:0xf bank_mask:0xf
	v_add_f32_dpp v23, v23, v23 row_mirror row_mask:0xf bank_mask:0xf
	v_pk_fma_f32 v[88:89], v[50:51], v[56:57], v[88:89] op_sel:[0,0,0] op_sel_hi:[0,1,1]
	v_pk_fma_f32 v[90:91], v[50:51], v[56:57], v[90:91] op_sel:[1,0,0] op_sel_hi:[1,1,1]
	v_add_f32_dpp v24, v24, v24 quad_perm:[2,3,0,1] row_mask:0xf bank_mask:0xf
	v_cndmask_b32_e64 v33, v33, v24, s[12:13]
	v_pk_fma_f32 v[2:3], v[44:45], v[22:23], v[84:85] op_sel:[0,0,0] op_sel_hi:[0,1,1] neg_lo:[1,0,0] neg_hi:[1,0,0]
	v_pk_fma_f32 v[4:5], v[44:45], v[22:23], v[86:87] op_sel:[1,0,0] op_sel_hi:[1,1,1] neg_lo:[1,0,0] neg_hi:[1,0,0]
	v_pk_fma_f32 v[6:7], v[46:47], v[22:23], v[88:89] op_sel:[0,0,0] op_sel_hi:[0,1,1] neg_lo:[1,0,0] neg_hi:[1,0,0]
	v_pk_fma_f32 v[8:9], v[46:47], v[22:23], v[90:91] op_sel:[1,0,0] op_sel_hi:[1,1,1] neg_lo:[1,0,0] neg_hi:[1,0,0]
	s_waitcnt lgkmcnt(0)
	v_pk_mul_f32 v[22:23], v[2:3], v[60:61] op_sel:[0,0] op_sel_hi:[1,0]
	v_pk_mul_f32 v[24:25], v[2:3], v[52:53] op_sel:[0,0] op_sel_hi:[1,0]
	v_pk_fma_f32 v[22:23], v[4:5], v[60:61], v[22:23] op_sel:[0,1,0] op_sel_hi:[1,1,1]
	v_pk_mul_f32 v[84:85], v[4:5], v[52:53] op_sel:[0,1] op_sel_hi:[1,1]
	v_pk_fma_f32 v[22:23], v[6:7], v[62:63], v[22:23] op_sel:[0,0,0] op_sel_hi:[1,0,1]
	v_pk_fma_f32 v[24:25], v[6:7], v[54:55], v[24:25] op_sel:[0,0,0] op_sel_hi:[1,0,1]
	v_pk_fma_f32 v[22:23], v[8:9], v[62:63], v[22:23] op_sel:[0,1,0] op_sel_hi:[1,1,1]
	v_pk_fma_f32 v[84:85], v[8:9], v[54:55], v[84:85] op_sel:[0,1,0] op_sel_hi:[1,1,1]
	v_pk_add_f32 v[24:25], v[24:25], v[84:85]
	v_add_f32_dpp v26, v26, v26 row_ror:12 row_mask:0xf bank_mask:0x5
	v_add_f32_dpp v27, v27, v27 row_ror:4 row_mask:0xf bank_mask:0xa
	v_add_f32_dpp v22, v22, v22 quad_perm:[1,0,3,2] row_mask:0xf bank_mask:0xf
	v_add_f32_dpp v23, v23, v23 quad_perm:[1,0,3,2] row_mask:0xf bank_mask:0xf
	v_pk_mul_f32 v[84:85], v[2:3], v[64:65] op_sel:[0,0] op_sel_hi:[1,0]
	v_pk_mul_f32 v[86:87], v[4:5], v[64:65] op_sel:[0,1] op_sel_hi:[1,1]
	v_mov_b32_dpp v26, v27 quad_perm:[0,1,2,3] row_mask:0xf bank_mask:0xa
	v_add_f32_dpp v22, v22, v22 quad_perm:[2,3,0,1] row_mask:0xf bank_mask:0xf
	v_add_f32_dpp v23, v23, v23 quad_perm:[2,3,0,1] row_mask:0xf bank_mask:0xf
	v_pk_mul_f32 v[88:89], v[6:7], v[66:67] op_sel:[0,0] op_sel_hi:[1,0]
	v_pk_mul_f32 v[90:91], v[8:9], v[66:67] op_sel:[0,1] op_sel_hi:[1,1]
	v_add_f32_dpp v26, v26, v26 row_ror:8 row_mask:0xf bank_mask:0xf
	v_add_f32_dpp v22, v22, v22 row_half_mirror row_mask:0xf bank_mask:0xf
	v_add_f32_dpp v23, v23, v23 row_half_mirror row_mask:0xf bank_mask:0xf
	v_pk_fma_f32 v[84:85], v[72:73], v[80:81], v[84:85] op_sel:[0,0,0] op_sel_hi:[0,1,1]
	v_pk_fma_f32 v[86:87], v[72:73], v[80:81], v[86:87] op_sel:[1,0,0] op_sel_hi:[1,1,1]
	v_add_f32_dpp v26, v26, v26 quad_perm:[1,0,3,2] row_mask:0xf bank_mask:0xf
	v_add_f32_dpp v22, v22, v22 row_mirror row_mask:0xf bank_mask:0xf
	v_add_f32_dpp v23, v23, v23 row_mirror row_mask:0xf bank_mask:0xf
	v_pk_fma_f32 v[88:89], v[74:75], v[80:81], v[88:89] op_sel:[0,0,0] op_sel_hi:[0,1,1]
	v_pk_fma_f32 v[90:91], v[74:75], v[80:81], v[90:91] op_sel:[1,0,0] op_sel_hi:[1,1,1]
	v_add_f32_dpp v26, v26, v26 quad_perm:[2,3,0,1] row_mask:0xf bank_mask:0xf
	v_cndmask_b32_e64 v33, v33, v26, s[14:15]
	v_pk_fma_f32 v[2:3], v[68:69], v[22:23], v[84:85] op_sel:[0,0,0] op_sel_hi:[0,1,1] neg_lo:[1,0,0] neg_hi:[1,0,0]
	v_pk_fma_f32 v[4:5], v[68:69], v[22:23], v[86:87] op_sel:[1,0,0] op_sel_hi:[1,1,1] neg_lo:[1,0,0] neg_hi:[1,0,0]
	v_pk_fma_f32 v[6:7], v[70:71], v[22:23], v[88:89] op_sel:[0,0,0] op_sel_hi:[0,1,1] neg_lo:[1,0,0] neg_hi:[1,0,0]
	v_pk_fma_f32 v[8:9], v[70:71], v[22:23], v[90:91] op_sel:[1,0,0] op_sel_hi:[1,1,1] neg_lo:[1,0,0] neg_hi:[1,0,0]
	s_waitcnt lgkmcnt(0)
	v_add_f32_dpp v24, v24, v24 row_ror:12 row_mask:0xf bank_mask:0x5
	v_add_f32_dpp v25, v25, v25 row_ror:4 row_mask:0xf bank_mask:0xa
	s_nop 1
	v_mov_b32_dpp v24, v25 quad_perm:[0,1,2,3] row_mask:0xf bank_mask:0xa
	s_nop 1
	v_add_f32_dpp v24, v24, v24 row_ror:8 row_mask:0xf bank_mask:0xf
	s_nop 1
	v_add_f32_dpp v24, v24, v24 quad_perm:[1,0,3,2] row_mask:0xf bank_mask:0xf
	s_nop 1
	v_add_f32_dpp v24, v24, v24 quad_perm:[2,3,0,1] row_mask:0xf bank_mask:0xf
	v_cndmask_b32_e64 v33, v33, v24, s[16:17]
	v_pk_mul_f32 v[26:27], v[2:3], v[76:77] op_sel:[0,0] op_sel_hi:[1,0]
	v_pk_mul_f32 v[84:85], v[4:5], v[76:77] op_sel:[0,1] op_sel_hi:[1,1]
	v_pk_fma_f32 v[26:27], v[6:7], v[78:79], v[26:27] op_sel:[0,0,0] op_sel_hi:[1,0,1]
	v_pk_fma_f32 v[84:85], v[8:9], v[78:79], v[84:85] op_sel:[0,1,0] op_sel_hi:[1,1,1]
	v_pk_add_f32 v[26:27], v[26:27], v[84:85]
	s_nop 1
	v_add_f32_dpp v26, v26, v26 row_ror:12 row_mask:0xf bank_mask:0x5
	v_add_f32_dpp v27, v27, v27 row_ror:4 row_mask:0xf bank_mask:0xa
	s_nop 1
	v_mov_b32_dpp v26, v27 quad_perm:[0,1,2,3] row_mask:0xf bank_mask:0xa
	s_nop 1
	v_add_f32_dpp v26, v26, v26 row_ror:8 row_mask:0xf bank_mask:0xf
	s_nop 1
	v_add_f32_dpp v26, v26, v26 quad_perm:[1,0,3,2] row_mask:0xf bank_mask:0xf
	s_nop 1
	v_add_f32_dpp v26, v26, v26 quad_perm:[2,3,0,1] row_mask:0xf bank_mask:0xf
	v_cndmask_b32_e32 v33, v33, v26, vcc
	v_lshl_add_u32 v35, s23, 12, v11
	s_add_i32 s22, s22, 1
	ds_write2st64_b32 v35, v30, v31 offset1:4
	ds_write2st64_b32 v35, v32, v33 offset0:8 offset1:12
	s_cmp_eq_u32 s22, 64
	s_waitcnt lgkmcnt(0)
	s_barrier
	s_cbranch_scc0 .LBB0_1750
	s_setprio 0
	s_lshl_b32 s0, s18, 4
	s_or_b32 s0, s0, s26
	s_ashr_i32 s1, s0, 31
	s_lshl_b64 s[0:1], s[0:1], 6
	s_lshl_b32 s2, s27, 5
	s_or_b32 s0, s0, s2
	v_or_b32_e32 v12, s0, v1
	v_mov_b32_e32 v13, s1
	v_lshlrev_b64 v[12:13], 8, v[12:13]
	v_lshl_add_u64 v[12:13], s[82:83], 0, v[12:13]
	v_mov_b32_e32 v11, 0
	v_lshl_add_u64 v[10:11], v[12:13], 0, v[10:11]
	s_mov_b64 s[0:1], 0x4100000
	v_lshl_add_u64 v[12:13], v[10:11], 0, s[0:1]
	v_add_co_u32_e32 v10, vcc, 0x4100000, v10
	s_nop 1
	v_addc_co_u32_e32 v11, vcc, 0, v11, vcc
	v_mov_b32_e32 v14, v2
	v_mov_b32_e32 v15, v4
	v_mov_b32_e32 v16, v6
	v_mov_b32_e32 v17, v8
	v_mov_b32_e32 v18, v3
	v_mov_b32_e32 v19, v5
	v_mov_b32_e32 v20, v7
	v_mov_b32_e32 v21, v9
	global_store_dwordx4 v[10:11], v[14:17], off
	global_store_dwordx4 v[12:13], v[18:21], off offset:256
